# lambda loads hoisted to kernel start (register-only compute_lam); P4 prologue wait removed; gates tiles write-through; L1 invalidate overlapped with barrier arrival
# speedup vs baseline: 1.0454x; 1.0191x over previous
.LBB0_5:
	s_or_b64 exec, exec, s[2:3]
	s_load_dwordx16 s[80:95], s[0:1], 0x0
	v_mbcnt_lo_u32_b32 v0, -1, 0
	v_mbcnt_hi_u32_b32 v231, -1, v0
	v_lshlrev_b32_e32 v246, 4, v231
	s_lshl_b32 s33, s63, 10
	v_mov_b32_e32 v0, v246
	s_waitcnt lgkmcnt(0)
	v_lshlrev_b32_e32 v232, 2, v231
	global_load_dword v233, v232, s[10:11]
	global_load_dword v234, v232, s[12:13]
	global_load_dword v235, v232, s[10:11] offset:256
	global_load_dword v240, v232, s[12:13] offset:256
	s_add_u32 s0, s90, s33
	s_barrier
	s_addc_u32 s1, s91, 0
	v_ashrrev_i32_e32 v1, 31, v0
	s_add_i32 s76, s33, 0
	v_lshl_add_u64 v[0:1], s[0:1], 0, v[0:1]
	s_add_i32 s0, s76, 0x20000
	s_mov_b32 s1, m0
	s_mov_b32 m0, s0
	s_nop 0
	global_load_lds_dwordx4 v[0:1], off
	s_mov_b32 m0, s1
	s_sub_i32 s0, s99, s98
	s_add_u32 s2, s66, 0x4000
	s_addc_u32 s3, s67, 0
	v_writelane_b32 v254, s2, 3
	s_mov_b32 s55, 0
	s_cmp_gt_i32 s0, 1
	v_writelane_b32 v254, s3, 4
	s_mov_b32 s0, 0
	s_cbranch_scc0 .LBB0_10
	v_mbcnt_lo_u32_b32 v0, -1, 0
	v_mbcnt_hi_u32_b32 v0, -1, v0
	v_readlane_b32 s0, v254, 2
	v_sub_u32_e32 v0, 0, v0
	s_nop 0
	v_cmp_eq_u32_e32 vcc, s0, v0
	s_getreg_b32 s0, hwreg(HW_REG_XCC_ID, 0, 4)
	s_and_b32 s55, s0, 15
	s_and_saveexec_b64 s[0:1], vcc
	s_cbranch_execz .LBB0_9
	s_mov_b64 s[2:3], exec
	v_mbcnt_lo_u32_b32 v0, s2, 0
	v_mbcnt_hi_u32_b32 v0, s3, v0
	v_cmp_eq_u32_e32 vcc, 0, v0
	s_and_b64 s[4:5], exec, vcc
	s_mov_b64 exec, s[4:5]
	s_cbranch_execz .LBB0_9
	s_bcnt1_i32_b64 s2, s[2:3]
	s_lshl_b32 s4, s55, 8
	v_mov_b32_e32 v1, s2
	v_readlane_b32 s2, v254, 3
	v_mov_b32_e32 v0, s4
	v_readlane_b32 s3, v254, 4
	s_nop 4
	global_atomic_add v0, v1, s[2:3] offset:1024

.LBB0_74:
	s_lshl_b32 s4, s55, 8
	v_readlane_b32 s6, v254, 3
	v_readlane_b32 s7, v254, 4
	s_add_u32 s4, s6, s4
	s_addc_u32 s5, s7, 0
	v_mov_b32_e32 v1, 0x1000
	v_mov_b32_e32 v3, 1
	global_atomic_add v3, v1, v3, s[4:5] offset:1024 sc0
	buffer_inv sc1
	v_cvt_f32_u32_e32 v1, v2
	v_sub_u32_e32 v4, 0, v2
	v_rcp_iflag_f32_e32 v1, v1
	s_nop 0
	v_mul_f32_e32 v1, 0x4f7ffffe, v1
	v_cvt_u32_f32_e32 v1, v1
	v_mul_lo_u32 v4, v4, v1
	v_mul_hi_u32 v4, v1, v4
	v_add_u32_e32 v1, v1, v4
	s_waitcnt vmcnt(0)
	v_mul_hi_u32 v1, v3, v1
	v_mul_lo_u32 v4, v1, v2
	v_sub_u32_e32 v4, v3, v4
	v_add_u32_e32 v5, 1, v1
	v_cmp_ge_u32_e32 vcc, v4, v2
	v_add_u32_e32 v3, 1, v3
	s_nop 0
	v_cndmask_b32_e32 v1, v1, v5, vcc
	v_sub_u32_e32 v5, v4, v2
	v_cndmask_b32_e32 v4, v4, v5, vcc
	v_add_u32_e32 v5, 1, v1
	v_cmp_ge_u32_e32 vcc, v4, v2
	s_nop 1
	v_cndmask_b32_e32 v1, v1, v5, vcc
	v_mul_lo_u32 v4, v2, v1
	v_add_u32_e32 v2, v4, v2
	v_cmp_ne_u32_e32 vcc, v3, v2
	s_and_saveexec_b64 s[6:7], vcc
	s_xor_b64 s[6:7], exec, s[6:7]
	s_cbranch_execz .LBB0_88
	s_waitcnt lgkmcnt(0)
	v_mov_b32_e32 v0, 0x2000
	global_load_dword v0, v0, s[4:5] offset:1024 sc1
	s_add_u32 s18, s4, 0x2400
	s_addc_u32 s19, s5, 0
	s_waitcnt vmcnt(0)
	v_cmp_eq_u32_e32 vcc, v0, v1
	s_and_saveexec_b64 s[8:9], vcc
	s_cbranch_execz .LBB0_87
	s_add_u32 s16, s66, 0x4200
	s_addc_u32 s17, s67, 0
	s_mov_b32 s30, 1
	s_mov_b64 s[20:21], 0
	v_mov_b32_e32 v0, 0
	s_branch .LBB0_78

.LBB0_87:
	s_or_b64 exec, exec, s[8:9]
	s_waitcnt vmcnt(0)
	s_waitcnt vmcnt(0)

.LBB0_105:
	s_or_b64 exec, exec, s[6:7]
	v_mov_b32_e32 v0, 0x2000
	v_mov_b32_e32 v1, 1
	s_waitcnt vmcnt(0)
	global_atomic_add v0, v1, s[4:5] offset:1024
	s_waitcnt vmcnt(0)

.Lp1e_gates:
	s_lshl_b32 s30, s6, 8
	s_lshl_b32 s31, s5, 6
	s_add_u32 s30, s30, s31
	s_lshl_b32 s30, s30, 12
	s_sub_u32 s31, s4, 16
	s_lshl_b32 s31, s31, 9
	s_lshl_b32 s23, s7, 6
	s_add_u32 s31, s31, s23
	s_lshl_b32 s23, s31, 1
	s_add_u32 s23, s23, s53
	s_add_u32 s30, s30, s31
	v_lshrrev_b32_e32 v165, 4, v231
	s_add_u32 s30, s74, s30
	s_addc_u32 s31, s75, 0
	v_lshl_add_u32 v165, v165, 5, s23
	s_mov_b32 s34, 12
	s_mov_b32 s35, 0x100
	ds_read_b128 v[92:95], v165
	ds_read_b128 v[88:91], v165 offset:16
	ds_read_b128 v[76:79], v165 offset:512
	ds_read_b128 v[72:75], v165 offset:528
	v_and_b32_e32 v152, 15, v231
	v_lshrrev_b32_e32 v162, 4, v231
	v_lshlrev_b32_e32 v152, s34, v152
	s_lshl_b32 s23, 16, s34
	v_lshl_or_b32 v152, v162, 4, v152
	s_lshl_b32 s4, s23, 1
	s_add_u32 s6, s4, s23
	s_lshl_b32 s5, 0x80, s34
	v_add_u32_e32 v162, s23, v152
	v_add_u32_e32 v163, s4, v152
	v_add_u32_e32 v164, s6, v152
	s_waitcnt lgkmcnt(0)
	v_pk_add_f32 v[140:141], v[140:141], v[92:93]
	v_pk_add_f32 v[142:143], v[142:143], v[94:95]
	v_pk_add_f32 v[136:137], v[136:137], v[88:89]
	v_pk_add_f32 v[138:139], v[138:139], v[90:91]
	v_mul_f32_e32 v140, 0xbfb8aa3b, v140
	v_mul_f32_e32 v141, 0xbfb8aa3b, v141
	v_mul_f32_e32 v142, 0xbfb8aa3b, v142
	v_mul_f32_e32 v143, 0xbfb8aa3b, v143
	v_mul_f32_e32 v136, 0xbfb8aa3b, v136
	v_mul_f32_e32 v137, 0xbfb8aa3b, v137
	v_mul_f32_e32 v138, 0xbfb8aa3b, v138
	v_mul_f32_e32 v139, 0xbfb8aa3b, v139
	v_exp_f32_e32 v140, v140
	v_exp_f32_e32 v141, v141
	v_exp_f32_e32 v142, v142
	v_exp_f32_e32 v143, v143
	v_exp_f32_e32 v136, v136
	v_exp_f32_e32 v137, v137
	v_exp_f32_e32 v138, v138
	v_exp_f32_e32 v139, v139
	v_add_f32_e32 v140, 1.0, v140
	v_add_f32_e32 v141, 1.0, v141
	v_add_f32_e32 v142, 1.0, v142
	v_add_f32_e32 v143, 1.0, v143
	v_add_f32_e32 v136, 1.0, v136
	v_add_f32_e32 v137, 1.0, v137
	v_add_f32_e32 v138, 1.0, v138
	v_add_f32_e32 v139, 1.0, v139
	v_rcp_f32_e32 v140, v140
	v_rcp_f32_e32 v141, v141
	v_rcp_f32_e32 v142, v142
	v_rcp_f32_e32 v143, v143
	v_rcp_f32_e32 v136, v136
	v_rcp_f32_e32 v137, v137
	v_rcp_f32_e32 v138, v138
	v_rcp_f32_e32 v139, v139
	s_nop 0
	v_cvt_pk_bf16_f32 v140, v140, v141
	v_cvt_pk_bf16_f32 v141, v142, v143
	v_cvt_pk_bf16_f32 v142, v136, v137
	v_cvt_pk_bf16_f32 v143, v138, v139
	global_store_dwordx4 v152, v[140:143], s[30:31] sc1
	v_pk_add_f32 v[124:125], v[124:125], v[92:93]
	v_pk_add_f32 v[126:127], v[126:127], v[94:95]
	v_pk_add_f32 v[120:121], v[120:121], v[88:89]
	v_pk_add_f32 v[122:123], v[122:123], v[90:91]
	v_mul_f32_e32 v124, 0xbfb8aa3b, v124
	v_mul_f32_e32 v125, 0xbfb8aa3b, v125
	v_mul_f32_e32 v126, 0xbfb8aa3b, v126
	v_mul_f32_e32 v127, 0xbfb8aa3b, v127
	v_mul_f32_e32 v120, 0xbfb8aa3b, v120
	v_mul_f32_e32 v121, 0xbfb8aa3b, v121
	v_mul_f32_e32 v122, 0xbfb8aa3b, v122
	v_mul_f32_e32 v123, 0xbfb8aa3b, v123
	v_exp_f32_e32 v124, v124
	v_exp_f32_e32 v125, v125
	v_exp_f32_e32 v126, v126
	v_exp_f32_e32 v127, v127
	v_exp_f32_e32 v120, v120
	v_exp_f32_e32 v121, v121
	v_exp_f32_e32 v122, v122
	v_exp_f32_e32 v123, v123
	v_add_f32_e32 v124, 1.0, v124
	v_add_f32_e32 v125, 1.0, v125
	v_add_f32_e32 v126, 1.0, v126
	v_add_f32_e32 v127, 1.0, v127
	v_add_f32_e32 v120, 1.0, v120
	v_add_f32_e32 v121, 1.0, v121
	v_add_f32_e32 v122, 1.0, v122
	v_add_f32_e32 v123, 1.0, v123
	v_rcp_f32_e32 v124, v124
	v_rcp_f32_e32 v125, v125
	v_rcp_f32_e32 v126, v126
	v_rcp_f32_e32 v127, v127
	v_rcp_f32_e32 v120, v120
	v_rcp_f32_e32 v121, v121
	v_rcp_f32_e32 v122, v122
	v_rcp_f32_e32 v123, v123
	s_nop 0
	v_cvt_pk_bf16_f32 v124, v124, v125
	v_cvt_pk_bf16_f32 v125, v126, v127
	v_cvt_pk_bf16_f32 v126, v120, v121
	v_cvt_pk_bf16_f32 v127, v122, v123
	global_store_dwordx4 v162, v[124:127], s[30:31] sc1
	v_pk_add_f32 v[108:109], v[108:109], v[92:93]
	v_pk_add_f32 v[110:111], v[110:111], v[94:95]
	v_pk_add_f32 v[104:105], v[104:105], v[88:89]
	v_pk_add_f32 v[106:107], v[106:107], v[90:91]
	v_mul_f32_e32 v108, 0xbfb8aa3b, v108
	v_mul_f32_e32 v109, 0xbfb8aa3b, v109
	v_mul_f32_e32 v110, 0xbfb8aa3b, v110
	v_mul_f32_e32 v111, 0xbfb8aa3b, v111
	v_mul_f32_e32 v104, 0xbfb8aa3b, v104
	v_mul_f32_e32 v105, 0xbfb8aa3b, v105
	v_mul_f32_e32 v106, 0xbfb8aa3b, v106
	v_mul_f32_e32 v107, 0xbfb8aa3b, v107
	v_exp_f32_e32 v108, v108
	v_exp_f32_e32 v109, v109
	v_exp_f32_e32 v110, v110
	v_exp_f32_e32 v111, v111
	v_exp_f32_e32 v104, v104
	v_exp_f32_e32 v105, v105
	v_exp_f32_e32 v106, v106
	v_exp_f32_e32 v107, v107
	v_add_f32_e32 v108, 1.0, v108
	v_add_f32_e32 v109, 1.0, v109
	v_add_f32_e32 v110, 1.0, v110
	v_add_f32_e32 v111, 1.0, v111
	v_add_f32_e32 v104, 1.0, v104
	v_add_f32_e32 v105, 1.0, v105
	v_add_f32_e32 v106, 1.0, v106
	v_add_f32_e32 v107, 1.0, v107
	v_rcp_f32_e32 v108, v108
	v_rcp_f32_e32 v109, v109
	v_rcp_f32_e32 v110, v110
	v_rcp_f32_e32 v111, v111
	v_rcp_f32_e32 v104, v104
	v_rcp_f32_e32 v105, v105
	v_rcp_f32_e32 v106, v106
	v_rcp_f32_e32 v107, v107
	s_nop 0
	v_cvt_pk_bf16_f32 v108, v108, v109
	v_cvt_pk_bf16_f32 v109, v110, v111
	v_cvt_pk_bf16_f32 v110, v104, v105
	v_cvt_pk_bf16_f32 v111, v106, v107
	global_store_dwordx4 v163, v[108:111], s[30:31] sc1
	v_pk_add_f32 v[84:85], v[84:85], v[92:93]
	v_pk_add_f32 v[86:87], v[86:87], v[94:95]
	v_pk_add_f32 v[80:81], v[80:81], v[88:89]
	v_pk_add_f32 v[82:83], v[82:83], v[90:91]
	v_mul_f32_e32 v84, 0xbfb8aa3b, v84
	v_mul_f32_e32 v85, 0xbfb8aa3b, v85
	v_mul_f32_e32 v86, 0xbfb8aa3b, v86
	v_mul_f32_e32 v87, 0xbfb8aa3b, v87
	v_mul_f32_e32 v80, 0xbfb8aa3b, v80
	v_mul_f32_e32 v81, 0xbfb8aa3b, v81
	v_mul_f32_e32 v82, 0xbfb8aa3b, v82
	v_mul_f32_e32 v83, 0xbfb8aa3b, v83
	v_exp_f32_e32 v84, v84
	v_exp_f32_e32 v85, v85
	v_exp_f32_e32 v86, v86
	v_exp_f32_e32 v87, v87
	v_exp_f32_e32 v80, v80
	v_exp_f32_e32 v81, v81
	v_exp_f32_e32 v82, v82
	v_exp_f32_e32 v83, v83
	v_add_f32_e32 v84, 1.0, v84
	v_add_f32_e32 v85, 1.0, v85
	v_add_f32_e32 v86, 1.0, v86
	v_add_f32_e32 v87, 1.0, v87
	v_add_f32_e32 v80, 1.0, v80
	v_add_f32_e32 v81, 1.0, v81
	v_add_f32_e32 v82, 1.0, v82
	v_add_f32_e32 v83, 1.0, v83
	v_rcp_f32_e32 v84, v84
	v_rcp_f32_e32 v85, v85
	v_rcp_f32_e32 v86, v86
	v_rcp_f32_e32 v87, v87
	v_rcp_f32_e32 v80, v80
	v_rcp_f32_e32 v81, v81
	v_rcp_f32_e32 v82, v82
	v_rcp_f32_e32 v83, v83
	s_nop 0
	v_cvt_pk_bf16_f32 v84, v84, v85
	v_cvt_pk_bf16_f32 v85, v86, v87
	v_cvt_pk_bf16_f32 v86, v80, v81
	v_cvt_pk_bf16_f32 v87, v82, v83
	global_store_dwordx4 v164, v[84:87], s[30:31] sc1
	s_add_u32 s30, s30, s35
	s_addc_u32 s31, s31, 0
	v_pk_add_f32 v[132:133], v[132:133], v[76:77]
	v_pk_add_f32 v[134:135], v[134:135], v[78:79]
	v_pk_add_f32 v[128:129], v[128:129], v[72:73]
	v_pk_add_f32 v[130:131], v[130:131], v[74:75]
	v_mul_f32_e32 v132, 0xbfb8aa3b, v132
	v_mul_f32_e32 v133, 0xbfb8aa3b, v133
	v_mul_f32_e32 v134, 0xbfb8aa3b, v134
	v_mul_f32_e32 v135, 0xbfb8aa3b, v135
	v_mul_f32_e32 v128, 0xbfb8aa3b, v128
	v_mul_f32_e32 v129, 0xbfb8aa3b, v129
	v_mul_f32_e32 v130, 0xbfb8aa3b, v130
	v_mul_f32_e32 v131, 0xbfb8aa3b, v131
	v_exp_f32_e32 v132, v132
	v_exp_f32_e32 v133, v133
	v_exp_f32_e32 v134, v134
	v_exp_f32_e32 v135, v135
	v_exp_f32_e32 v128, v128
	v_exp_f32_e32 v129, v129
	v_exp_f32_e32 v130, v130
	v_exp_f32_e32 v131, v131
	v_add_f32_e32 v132, 1.0, v132
	v_add_f32_e32 v133, 1.0, v133
	v_add_f32_e32 v134, 1.0, v134
	v_add_f32_e32 v135, 1.0, v135
	v_add_f32_e32 v128, 1.0, v128
	v_add_f32_e32 v129, 1.0, v129
	v_add_f32_e32 v130, 1.0, v130
	v_add_f32_e32 v131, 1.0, v131
	v_rcp_f32_e32 v132, v132
	v_rcp_f32_e32 v133, v133
	v_rcp_f32_e32 v134, v134
	v_rcp_f32_e32 v135, v135
	v_rcp_f32_e32 v128, v128
	v_rcp_f32_e32 v129, v129
	v_rcp_f32_e32 v130, v130
	v_rcp_f32_e32 v131, v131
	s_nop 0
	v_cvt_pk_bf16_f32 v132, v132, v133
	v_cvt_pk_bf16_f32 v133, v134, v135
	v_cvt_pk_bf16_f32 v134, v128, v129
	v_cvt_pk_bf16_f32 v135, v130, v131
	global_store_dwordx4 v152, v[132:135], s[30:31] sc1
	v_pk_add_f32 v[116:117], v[116:117], v[76:77]
	v_pk_add_f32 v[118:119], v[118:119], v[78:79]
	v_pk_add_f32 v[112:113], v[112:113], v[72:73]
	v_pk_add_f32 v[114:115], v[114:115], v[74:75]
	v_mul_f32_e32 v116, 0xbfb8aa3b, v116
	v_mul_f32_e32 v117, 0xbfb8aa3b, v117
	v_mul_f32_e32 v118, 0xbfb8aa3b, v118
	v_mul_f32_e32 v119, 0xbfb8aa3b, v119
	v_mul_f32_e32 v112, 0xbfb8aa3b, v112
	v_mul_f32_e32 v113, 0xbfb8aa3b, v113
	v_mul_f32_e32 v114, 0xbfb8aa3b, v114
	v_mul_f32_e32 v115, 0xbfb8aa3b, v115
	v_exp_f32_e32 v116, v116
	v_exp_f32_e32 v117, v117
	v_exp_f32_e32 v118, v118
	v_exp_f32_e32 v119, v119
	v_exp_f32_e32 v112, v112
	v_exp_f32_e32 v113, v113
	v_exp_f32_e32 v114, v114
	v_exp_f32_e32 v115, v115
	v_add_f32_e32 v116, 1.0, v116
	v_add_f32_e32 v117, 1.0, v117
	v_add_f32_e32 v118, 1.0, v118
	v_add_f32_e32 v119, 1.0, v119
	v_add_f32_e32 v112, 1.0, v112
	v_add_f32_e32 v113, 1.0, v113
	v_add_f32_e32 v114, 1.0, v114
	v_add_f32_e32 v115, 1.0, v115
	v_rcp_f32_e32 v116, v116
	v_rcp_f32_e32 v117, v117
	v_rcp_f32_e32 v118, v118
	v_rcp_f32_e32 v119, v119
	v_rcp_f32_e32 v112, v112
	v_rcp_f32_e32 v113, v113
	v_rcp_f32_e32 v114, v114
	v_rcp_f32_e32 v115, v115
	s_nop 0
	v_cvt_pk_bf16_f32 v116, v116, v117
	v_cvt_pk_bf16_f32 v117, v118, v119
	v_cvt_pk_bf16_f32 v118, v112, v113
	v_cvt_pk_bf16_f32 v119, v114, v115
	global_store_dwordx4 v162, v[116:119], s[30:31] sc1
	v_pk_add_f32 v[100:101], v[100:101], v[76:77]
	v_pk_add_f32 v[102:103], v[102:103], v[78:79]
	v_pk_add_f32 v[96:97], v[96:97], v[72:73]
	v_pk_add_f32 v[98:99], v[98:99], v[74:75]
	v_mul_f32_e32 v100, 0xbfb8aa3b, v100
	v_mul_f32_e32 v101, 0xbfb8aa3b, v101
	v_mul_f32_e32 v102, 0xbfb8aa3b, v102
	v_mul_f32_e32 v103, 0xbfb8aa3b, v103
	v_mul_f32_e32 v96, 0xbfb8aa3b, v96
	v_mul_f32_e32 v97, 0xbfb8aa3b, v97
	v_mul_f32_e32 v98, 0xbfb8aa3b, v98
	v_mul_f32_e32 v99, 0xbfb8aa3b, v99
	v_exp_f32_e32 v100, v100
	v_exp_f32_e32 v101, v101
	v_exp_f32_e32 v102, v102
	v_exp_f32_e32 v103, v103
	v_exp_f32_e32 v96, v96
	v_exp_f32_e32 v97, v97
	v_exp_f32_e32 v98, v98
	v_exp_f32_e32 v99, v99
	v_add_f32_e32 v100, 1.0, v100
	v_add_f32_e32 v101, 1.0, v101
	v_add_f32_e32 v102, 1.0, v102
	v_add_f32_e32 v103, 1.0, v103
	v_add_f32_e32 v96, 1.0, v96
	v_add_f32_e32 v97, 1.0, v97
	v_add_f32_e32 v98, 1.0, v98
	v_add_f32_e32 v99, 1.0, v99
	v_rcp_f32_e32 v100, v100
	v_rcp_f32_e32 v101, v101
	v_rcp_f32_e32 v102, v102
	v_rcp_f32_e32 v103, v103
	v_rcp_f32_e32 v96, v96
	v_rcp_f32_e32 v97, v97
	v_rcp_f32_e32 v98, v98
	v_rcp_f32_e32 v99, v99
	s_nop 0
	v_cvt_pk_bf16_f32 v100, v100, v101
	v_cvt_pk_bf16_f32 v101, v102, v103
	v_cvt_pk_bf16_f32 v102, v96, v97
	v_cvt_pk_bf16_f32 v103, v98, v99
	global_store_dwordx4 v163, v[100:103], s[30:31] sc1
	v_pk_add_f32 v[68:69], v[68:69], v[76:77]
	v_pk_add_f32 v[70:71], v[70:71], v[78:79]
	v_pk_add_f32 v[64:65], v[64:65], v[72:73]
	v_pk_add_f32 v[66:67], v[66:67], v[74:75]
	v_mul_f32_e32 v68, 0xbfb8aa3b, v68
	v_mul_f32_e32 v69, 0xbfb8aa3b, v69
	v_mul_f32_e32 v70, 0xbfb8aa3b, v70
	v_mul_f32_e32 v71, 0xbfb8aa3b, v71
	v_mul_f32_e32 v64, 0xbfb8aa3b, v64
	v_mul_f32_e32 v65, 0xbfb8aa3b, v65
	v_mul_f32_e32 v66, 0xbfb8aa3b, v66
	v_mul_f32_e32 v67, 0xbfb8aa3b, v67
	v_exp_f32_e32 v68, v68
	v_exp_f32_e32 v69, v69
	v_exp_f32_e32 v70, v70
	v_exp_f32_e32 v71, v71
	v_exp_f32_e32 v64, v64
	v_exp_f32_e32 v65, v65
	v_exp_f32_e32 v66, v66
	v_exp_f32_e32 v67, v67
	v_add_f32_e32 v68, 1.0, v68
	v_add_f32_e32 v69, 1.0, v69
	v_add_f32_e32 v70, 1.0, v70
	v_add_f32_e32 v71, 1.0, v71
	v_add_f32_e32 v64, 1.0, v64
	v_add_f32_e32 v65, 1.0, v65
	v_add_f32_e32 v66, 1.0, v66
	v_add_f32_e32 v67, 1.0, v67
	v_rcp_f32_e32 v68, v68
	v_rcp_f32_e32 v69, v69
	v_rcp_f32_e32 v70, v70
	v_rcp_f32_e32 v71, v71
	v_rcp_f32_e32 v64, v64
	v_rcp_f32_e32 v65, v65
	v_rcp_f32_e32 v66, v66
	v_rcp_f32_e32 v67, v67
	s_nop 0
	v_cvt_pk_bf16_f32 v68, v68, v69
	v_cvt_pk_bf16_f32 v69, v70, v71
	v_cvt_pk_bf16_f32 v70, v64, v65
	v_cvt_pk_bf16_f32 v71, v66, v67
	global_store_dwordx4 v164, v[68:71], s[30:31] sc1
	s_sub_u32 s30, s30, s35
	s_subb_u32 s31, s31, 0
	s_add_u32 s30, s30, s5
	s_addc_u32 s31, s31, 0
	v_pk_add_f32 v[60:61], v[60:61], v[92:93]
	v_pk_add_f32 v[62:63], v[62:63], v[94:95]
	v_pk_add_f32 v[56:57], v[56:57], v[88:89]
	v_pk_add_f32 v[58:59], v[58:59], v[90:91]
	v_mul_f32_e32 v60, 0xbfb8aa3b, v60
	v_mul_f32_e32 v61, 0xbfb8aa3b, v61
	v_mul_f32_e32 v62, 0xbfb8aa3b, v62
	v_mul_f32_e32 v63, 0xbfb8aa3b, v63
	v_mul_f32_e32 v56, 0xbfb8aa3b, v56
	v_mul_f32_e32 v57, 0xbfb8aa3b, v57
	v_mul_f32_e32 v58, 0xbfb8aa3b, v58
	v_mul_f32_e32 v59, 0xbfb8aa3b, v59
	v_exp_f32_e32 v60, v60
	v_exp_f32_e32 v61, v61
	v_exp_f32_e32 v62, v62
	v_exp_f32_e32 v63, v63
	v_exp_f32_e32 v56, v56
	v_exp_f32_e32 v57, v57
	v_exp_f32_e32 v58, v58
	v_exp_f32_e32 v59, v59
	v_add_f32_e32 v60, 1.0, v60
	v_add_f32_e32 v61, 1.0, v61
	v_add_f32_e32 v62, 1.0, v62
	v_add_f32_e32 v63, 1.0, v63
	v_add_f32_e32 v56, 1.0, v56
	v_add_f32_e32 v57, 1.0, v57
	v_add_f32_e32 v58, 1.0, v58
	v_add_f32_e32 v59, 1.0, v59
	v_rcp_f32_e32 v60, v60
	v_rcp_f32_e32 v61, v61
	v_rcp_f32_e32 v62, v62
	v_rcp_f32_e32 v63, v63
	v_rcp_f32_e32 v56, v56
	v_rcp_f32_e32 v57, v57
	v_rcp_f32_e32 v58, v58
	v_rcp_f32_e32 v59, v59
	s_nop 0
	v_cvt_pk_bf16_f32 v60, v60, v61
	v_cvt_pk_bf16_f32 v61, v62, v63
	v_cvt_pk_bf16_f32 v62, v56, v57
	v_cvt_pk_bf16_f32 v63, v58, v59
	global_store_dwordx4 v152, v[60:63], s[30:31] sc1
	v_pk_add_f32 v[44:45], v[44:45], v[92:93]
	v_pk_add_f32 v[46:47], v[46:47], v[94:95]
	v_pk_add_f32 v[40:41], v[40:41], v[88:89]
	v_pk_add_f32 v[42:43], v[42:43], v[90:91]
	v_mul_f32_e32 v44, 0xbfb8aa3b, v44
	v_mul_f32_e32 v45, 0xbfb8aa3b, v45
	v_mul_f32_e32 v46, 0xbfb8aa3b, v46
	v_mul_f32_e32 v47, 0xbfb8aa3b, v47
	v_mul_f32_e32 v40, 0xbfb8aa3b, v40
	v_mul_f32_e32 v41, 0xbfb8aa3b, v41
	v_mul_f32_e32 v42, 0xbfb8aa3b, v42
	v_mul_f32_e32 v43, 0xbfb8aa3b, v43
	v_exp_f32_e32 v44, v44
	v_exp_f32_e32 v45, v45
	v_exp_f32_e32 v46, v46
	v_exp_f32_e32 v47, v47
	v_exp_f32_e32 v40, v40
	v_exp_f32_e32 v41, v41
	v_exp_f32_e32 v42, v42
	v_exp_f32_e32 v43, v43
	v_add_f32_e32 v44, 1.0, v44
	v_add_f32_e32 v45, 1.0, v45
	v_add_f32_e32 v46, 1.0, v46
	v_add_f32_e32 v47, 1.0, v47
	v_add_f32_e32 v40, 1.0, v40
	v_add_f32_e32 v41, 1.0, v41
	v_add_f32_e32 v42, 1.0, v42
	v_add_f32_e32 v43, 1.0, v43
	v_rcp_f32_e32 v44, v44
	v_rcp_f32_e32 v45, v45
	v_rcp_f32_e32 v46, v46
	v_rcp_f32_e32 v47, v47
	v_rcp_f32_e32 v40, v40
	v_rcp_f32_e32 v41, v41
	v_rcp_f32_e32 v42, v42
	v_rcp_f32_e32 v43, v43
	s_nop 0
	v_cvt_pk_bf16_f32 v44, v44, v45
	v_cvt_pk_bf16_f32 v45, v46, v47
	v_cvt_pk_bf16_f32 v46, v40, v41
	v_cvt_pk_bf16_f32 v47, v42, v43
	global_store_dwordx4 v162, v[44:47], s[30:31] sc1
	v_pk_add_f32 v[28:29], v[28:29], v[92:93]
	v_pk_add_f32 v[30:31], v[30:31], v[94:95]
	v_pk_add_f32 v[24:25], v[24:25], v[88:89]
	v_pk_add_f32 v[26:27], v[26:27], v[90:91]
	v_mul_f32_e32 v28, 0xbfb8aa3b, v28
	v_mul_f32_e32 v29, 0xbfb8aa3b, v29
	v_mul_f32_e32 v30, 0xbfb8aa3b, v30
	v_mul_f32_e32 v31, 0xbfb8aa3b, v31
	v_mul_f32_e32 v24, 0xbfb8aa3b, v24
	v_mul_f32_e32 v25, 0xbfb8aa3b, v25
	v_mul_f32_e32 v26, 0xbfb8aa3b, v26
	v_mul_f32_e32 v27, 0xbfb8aa3b, v27
	v_exp_f32_e32 v28, v28
	v_exp_f32_e32 v29, v29
	v_exp_f32_e32 v30, v30
	v_exp_f32_e32 v31, v31
	v_exp_f32_e32 v24, v24
	v_exp_f32_e32 v25, v25
	v_exp_f32_e32 v26, v26
	v_exp_f32_e32 v27, v27
	v_add_f32_e32 v28, 1.0, v28
	v_add_f32_e32 v29, 1.0, v29
	v_add_f32_e32 v30, 1.0, v30
	v_add_f32_e32 v31, 1.0, v31
	v_add_f32_e32 v24, 1.0, v24
	v_add_f32_e32 v25, 1.0, v25
	v_add_f32_e32 v26, 1.0, v26
	v_add_f32_e32 v27, 1.0, v27
	v_rcp_f32_e32 v28, v28
	v_rcp_f32_e32 v29, v29
	v_rcp_f32_e32 v30, v30
	v_rcp_f32_e32 v31, v31
	v_rcp_f32_e32 v24, v24
	v_rcp_f32_e32 v25, v25
	v_rcp_f32_e32 v26, v26
	v_rcp_f32_e32 v27, v27
	s_nop 0
	v_cvt_pk_bf16_f32 v28, v28, v29
	v_cvt_pk_bf16_f32 v29, v30, v31
	v_cvt_pk_bf16_f32 v30, v24, v25
	v_cvt_pk_bf16_f32 v31, v26, v27
	global_store_dwordx4 v163, v[28:31], s[30:31] sc1
	v_pk_add_f32 v[12:13], v[12:13], v[92:93]
	v_pk_add_f32 v[14:15], v[14:15], v[94:95]
	v_pk_add_f32 v[8:9], v[8:9], v[88:89]
	v_pk_add_f32 v[10:11], v[10:11], v[90:91]
	v_mul_f32_e32 v12, 0xbfb8aa3b, v12
	v_mul_f32_e32 v13, 0xbfb8aa3b, v13
	v_mul_f32_e32 v14, 0xbfb8aa3b, v14
	v_mul_f32_e32 v15, 0xbfb8aa3b, v15
	v_mul_f32_e32 v8, 0xbfb8aa3b, v8
	v_mul_f32_e32 v9, 0xbfb8aa3b, v9
	v_mul_f32_e32 v10, 0xbfb8aa3b, v10
	v_mul_f32_e32 v11, 0xbfb8aa3b, v11
	v_exp_f32_e32 v12, v12
	v_exp_f32_e32 v13, v13
	v_exp_f32_e32 v14, v14
	v_exp_f32_e32 v15, v15
	v_exp_f32_e32 v8, v8
	v_exp_f32_e32 v9, v9
	v_exp_f32_e32 v10, v10
	v_exp_f32_e32 v11, v11
	v_add_f32_e32 v12, 1.0, v12
	v_add_f32_e32 v13, 1.0, v13
	v_add_f32_e32 v14, 1.0, v14
	v_add_f32_e32 v15, 1.0, v15
	v_add_f32_e32 v8, 1.0, v8
	v_add_f32_e32 v9, 1.0, v9
	v_add_f32_e32 v10, 1.0, v10
	v_add_f32_e32 v11, 1.0, v11
	v_rcp_f32_e32 v12, v12
	v_rcp_f32_e32 v13, v13
	v_rcp_f32_e32 v14, v14
	v_rcp_f32_e32 v15, v15
	v_rcp_f32_e32 v8, v8
	v_rcp_f32_e32 v9, v9
	v_rcp_f32_e32 v10, v10
	v_rcp_f32_e32 v11, v11
	s_nop 0
	v_cvt_pk_bf16_f32 v12, v12, v13
	v_cvt_pk_bf16_f32 v13, v14, v15
	v_cvt_pk_bf16_f32 v14, v8, v9
	v_cvt_pk_bf16_f32 v15, v10, v11
	global_store_dwordx4 v164, v[12:15], s[30:31] sc1
	s_add_u32 s30, s30, s35
	s_addc_u32 s31, s31, 0
	v_pk_add_f32 v[52:53], v[52:53], v[76:77]
	v_pk_add_f32 v[54:55], v[54:55], v[78:79]
	v_pk_add_f32 v[48:49], v[48:49], v[72:73]
	v_pk_add_f32 v[50:51], v[50:51], v[74:75]
	v_mul_f32_e32 v52, 0xbfb8aa3b, v52
	v_mul_f32_e32 v53, 0xbfb8aa3b, v53
	v_mul_f32_e32 v54, 0xbfb8aa3b, v54
	v_mul_f32_e32 v55, 0xbfb8aa3b, v55
	v_mul_f32_e32 v48, 0xbfb8aa3b, v48
	v_mul_f32_e32 v49, 0xbfb8aa3b, v49
	v_mul_f32_e32 v50, 0xbfb8aa3b, v50
	v_mul_f32_e32 v51, 0xbfb8aa3b, v51
	v_exp_f32_e32 v52, v52
	v_exp_f32_e32 v53, v53
	v_exp_f32_e32 v54, v54
	v_exp_f32_e32 v55, v55
	v_exp_f32_e32 v48, v48
	v_exp_f32_e32 v49, v49
	v_exp_f32_e32 v50, v50
	v_exp_f32_e32 v51, v51
	v_add_f32_e32 v52, 1.0, v52
	v_add_f32_e32 v53, 1.0, v53
	v_add_f32_e32 v54, 1.0, v54
	v_add_f32_e32 v55, 1.0, v55
	v_add_f32_e32 v48, 1.0, v48
	v_add_f32_e32 v49, 1.0, v49
	v_add_f32_e32 v50, 1.0, v50
	v_add_f32_e32 v51, 1.0, v51
	v_rcp_f32_e32 v52, v52
	v_rcp_f32_e32 v53, v53
	v_rcp_f32_e32 v54, v54
	v_rcp_f32_e32 v55, v55
	v_rcp_f32_e32 v48, v48
	v_rcp_f32_e32 v49, v49
	v_rcp_f32_e32 v50, v50
	v_rcp_f32_e32 v51, v51
	s_nop 0
	v_cvt_pk_bf16_f32 v52, v52, v53
	v_cvt_pk_bf16_f32 v53, v54, v55
	v_cvt_pk_bf16_f32 v54, v48, v49
	v_cvt_pk_bf16_f32 v55, v50, v51
	global_store_dwordx4 v152, v[52:55], s[30:31] sc1
	v_pk_add_f32 v[36:37], v[36:37], v[76:77]
	v_pk_add_f32 v[38:39], v[38:39], v[78:79]
	v_pk_add_f32 v[32:33], v[32:33], v[72:73]
	v_pk_add_f32 v[34:35], v[34:35], v[74:75]
	v_mul_f32_e32 v36, 0xbfb8aa3b, v36
	v_mul_f32_e32 v37, 0xbfb8aa3b, v37
	v_mul_f32_e32 v38, 0xbfb8aa3b, v38
	v_mul_f32_e32 v39, 0xbfb8aa3b, v39
	v_mul_f32_e32 v32, 0xbfb8aa3b, v32
	v_mul_f32_e32 v33, 0xbfb8aa3b, v33
	v_mul_f32_e32 v34, 0xbfb8aa3b, v34
	v_mul_f32_e32 v35, 0xbfb8aa3b, v35
	v_exp_f32_e32 v36, v36
	v_exp_f32_e32 v37, v37
	v_exp_f32_e32 v38, v38
	v_exp_f32_e32 v39, v39
	v_exp_f32_e32 v32, v32
	v_exp_f32_e32 v33, v33
	v_exp_f32_e32 v34, v34
	v_exp_f32_e32 v35, v35
	v_add_f32_e32 v36, 1.0, v36
	v_add_f32_e32 v37, 1.0, v37
	v_add_f32_e32 v38, 1.0, v38
	v_add_f32_e32 v39, 1.0, v39
	v_add_f32_e32 v32, 1.0, v32
	v_add_f32_e32 v33, 1.0, v33
	v_add_f32_e32 v34, 1.0, v34
	v_add_f32_e32 v35, 1.0, v35
	v_rcp_f32_e32 v36, v36
	v_rcp_f32_e32 v37, v37
	v_rcp_f32_e32 v38, v38
	v_rcp_f32_e32 v39, v39
	v_rcp_f32_e32 v32, v32
	v_rcp_f32_e32 v33, v33
	v_rcp_f32_e32 v34, v34
	v_rcp_f32_e32 v35, v35
	s_nop 0
	v_cvt_pk_bf16_f32 v36, v36, v37
	v_cvt_pk_bf16_f32 v37, v38, v39
	v_cvt_pk_bf16_f32 v38, v32, v33
	v_cvt_pk_bf16_f32 v39, v34, v35
	global_store_dwordx4 v162, v[36:39], s[30:31] sc1
	v_pk_add_f32 v[20:21], v[20:21], v[76:77]
	v_pk_add_f32 v[22:23], v[22:23], v[78:79]
	v_pk_add_f32 v[16:17], v[16:17], v[72:73]
	v_pk_add_f32 v[18:19], v[18:19], v[74:75]
	v_mul_f32_e32 v20, 0xbfb8aa3b, v20
	v_mul_f32_e32 v21, 0xbfb8aa3b, v21
	v_mul_f32_e32 v22, 0xbfb8aa3b, v22
	v_mul_f32_e32 v23, 0xbfb8aa3b, v23
	v_mul_f32_e32 v16, 0xbfb8aa3b, v16
	v_mul_f32_e32 v17, 0xbfb8aa3b, v17
	v_mul_f32_e32 v18, 0xbfb8aa3b, v18
	v_mul_f32_e32 v19, 0xbfb8aa3b, v19
	v_exp_f32_e32 v20, v20
	v_exp_f32_e32 v21, v21
	v_exp_f32_e32 v22, v22
	v_exp_f32_e32 v23, v23
	v_exp_f32_e32 v16, v16
	v_exp_f32_e32 v17, v17
	v_exp_f32_e32 v18, v18
	v_exp_f32_e32 v19, v19
	v_add_f32_e32 v20, 1.0, v20
	v_add_f32_e32 v21, 1.0, v21
	v_add_f32_e32 v22, 1.0, v22
	v_add_f32_e32 v23, 1.0, v23
	v_add_f32_e32 v16, 1.0, v16
	v_add_f32_e32 v17, 1.0, v17
	v_add_f32_e32 v18, 1.0, v18
	v_add_f32_e32 v19, 1.0, v19
	v_rcp_f32_e32 v20, v20
	v_rcp_f32_e32 v21, v21
	v_rcp_f32_e32 v22, v22
	v_rcp_f32_e32 v23, v23
	v_rcp_f32_e32 v16, v16
	v_rcp_f32_e32 v17, v17
	v_rcp_f32_e32 v18, v18
	v_rcp_f32_e32 v19, v19
	s_nop 0
	v_cvt_pk_bf16_f32 v20, v20, v21
	v_cvt_pk_bf16_f32 v21, v22, v23
	v_cvt_pk_bf16_f32 v22, v16, v17
	v_cvt_pk_bf16_f32 v23, v18, v19
	global_store_dwordx4 v163, v[20:23], s[30:31] sc1
	v_pk_add_f32 v[4:5], v[4:5], v[76:77]
	v_pk_add_f32 v[6:7], v[6:7], v[78:79]
	v_pk_add_f32 v[0:1], v[0:1], v[72:73]
	v_pk_add_f32 v[2:3], v[2:3], v[74:75]
	v_mul_f32_e32 v4, 0xbfb8aa3b, v4
	v_mul_f32_e32 v5, 0xbfb8aa3b, v5
	v_mul_f32_e32 v6, 0xbfb8aa3b, v6
	v_mul_f32_e32 v7, 0xbfb8aa3b, v7
	v_mul_f32_e32 v0, 0xbfb8aa3b, v0
	v_mul_f32_e32 v1, 0xbfb8aa3b, v1
	v_mul_f32_e32 v2, 0xbfb8aa3b, v2
	v_mul_f32_e32 v3, 0xbfb8aa3b, v3
	v_exp_f32_e32 v4, v4
	v_exp_f32_e32 v5, v5
	v_exp_f32_e32 v6, v6
	v_exp_f32_e32 v7, v7
	v_exp_f32_e32 v0, v0
	v_exp_f32_e32 v1, v1
	v_exp_f32_e32 v2, v2
	v_exp_f32_e32 v3, v3
	v_add_f32_e32 v4, 1.0, v4
	v_add_f32_e32 v5, 1.0, v5
	v_add_f32_e32 v6, 1.0, v6
	v_add_f32_e32 v7, 1.0, v7
	v_add_f32_e32 v0, 1.0, v0
	v_add_f32_e32 v1, 1.0, v1
	v_add_f32_e32 v2, 1.0, v2
	v_add_f32_e32 v3, 1.0, v3
	v_rcp_f32_e32 v4, v4
	v_rcp_f32_e32 v5, v5
	v_rcp_f32_e32 v6, v6
	v_rcp_f32_e32 v7, v7
	v_rcp_f32_e32 v0, v0
	v_rcp_f32_e32 v1, v1
	v_rcp_f32_e32 v2, v2
	v_rcp_f32_e32 v3, v3
	s_nop 0
	v_cvt_pk_bf16_f32 v4, v4, v5
	v_cvt_pk_bf16_f32 v5, v6, v7
	v_cvt_pk_bf16_f32 v6, v0, v1
	v_cvt_pk_bf16_f32 v7, v2, v3
	global_store_dwordx4 v164, v[4:7], s[30:31] sc1

.LBB0_258:
	v_readlane_b32 s2, v254, 8
	s_lshl_b32 s2, s2, 8
	v_readlane_b32 s4, v254, 3
	v_readlane_b32 s5, v254, 4
	s_add_u32 s2, s4, s2
	s_addc_u32 s3, s5, 0
	v_mov_b32_e32 v1, 0x1000
	v_mov_b32_e32 v3, 1
	global_atomic_add v3, v1, v3, s[2:3] offset:1024 sc0
	buffer_inv sc1
	v_cvt_f32_u32_e32 v1, v2
	v_sub_u32_e32 v4, 0, v2
	v_rcp_iflag_f32_e32 v1, v1
	s_nop 0
	v_mul_f32_e32 v1, 0x4f7ffffe, v1
	v_cvt_u32_f32_e32 v1, v1
	v_mul_lo_u32 v4, v4, v1
	v_mul_hi_u32 v4, v1, v4
	v_add_u32_e32 v1, v1, v4
	s_waitcnt vmcnt(0)
	v_mul_hi_u32 v1, v3, v1
	v_mul_lo_u32 v4, v1, v2
	v_sub_u32_e32 v4, v3, v4
	v_add_u32_e32 v5, 1, v1
	v_cmp_ge_u32_e32 vcc, v4, v2
	v_add_u32_e32 v3, 1, v3
	s_nop 0
	v_cndmask_b32_e32 v1, v1, v5, vcc
	v_sub_u32_e32 v5, v4, v2
	v_cndmask_b32_e32 v4, v4, v5, vcc
	v_add_u32_e32 v5, 1, v1
	v_cmp_ge_u32_e32 vcc, v4, v2
	s_nop 1
	v_cndmask_b32_e32 v1, v1, v5, vcc
	v_mul_lo_u32 v4, v2, v1
	v_add_u32_e32 v2, v4, v2
	v_cmp_ne_u32_e32 vcc, v3, v2
	s_and_saveexec_b64 s[4:5], vcc
	s_xor_b64 s[4:5], exec, s[4:5]
	s_cbranch_execz .LBB0_272
	s_waitcnt lgkmcnt(0)
	v_mov_b32_e32 v0, 0x2000
	global_load_dword v0, v0, s[2:3] offset:1024 sc1
	s_add_u32 s16, s2, 0x2400
	s_addc_u32 s17, s3, 0
	s_waitcnt vmcnt(0)
	v_cmp_eq_u32_e32 vcc, v0, v1
	s_and_saveexec_b64 s[6:7], vcc
	s_cbranch_execz .LBB0_271
	s_add_u32 s8, s66, 0x4200
	s_addc_u32 s9, s67, 0
	s_mov_b32 s28, 1
	s_mov_b64 s[18:19], 0
	v_mov_b32_e32 v0, 0
	s_branch .LBB0_262

.LBB0_271:
	s_or_b64 exec, exec, s[6:7]
	s_waitcnt vmcnt(0)
	s_waitcnt vmcnt(0)

.LBB0_289:
	s_or_b64 exec, exec, s[4:5]
	v_mov_b32_e32 v0, 0x2000
	v_mov_b32_e32 v1, 1
	s_waitcnt vmcnt(0)
	global_atomic_add v0, v1, s[2:3] offset:1024
	s_waitcnt vmcnt(0)

.LBB0_379:
	v_mbcnt_lo_u32_b32 v34, -1, 0
	v_mbcnt_hi_u32_b32 v34, -1, v34
	v_readlane_b32 s98, v255, 38
	v_readlane_b32 s56, v255, 34
	v_readlane_b32 s70, v255, 47
	v_readlane_b32 s78, v255, 36
	v_readlane_b32 s86, v255, 45
	v_sub_u32_e32 v34, 0, v34
	v_readlane_b32 s4, v254, 2
	v_readlane_b32 s72, v255, 32
	v_readlane_b32 s73, v255, 33
	v_readlane_b32 s99, v255, 39
	v_readlane_b32 s57, v255, 35
	s_mov_b32 s68, s95
	v_readlane_b32 s71, v255, 48
	v_readlane_b32 s79, v255, 37
	v_readlane_b32 s30, v255, 40
	v_readlane_b32 s31, v255, 41
	v_readlane_b32 s34, v255, 42
	v_readlane_b32 s87, v255, 46
	s_mov_b64 s[88:89], 0x80
	v_cmp_eq_u32_e32 vcc, s4, v34
	v_mov_b32_e32 v95, 0xf0000
	s_and_saveexec_b64 s[4:5], vcc
	s_cbranch_execz .LBB0_384
	v_mov_b32_e32 v34, s69
	ds_read_b32 v34, v34
	v_readlane_b32 s7, v254, 32
	v_readlane_b32 s8, v254, 34
	v_mov_b32_e32 v95, 0xf0000
	s_waitcnt lgkmcnt(0)
	v_readfirstlane_b32 s6, v34
	s_and_b32 s7, s6, s7
	s_cmp_eq_u32 s7, 0
	v_readlane_b32 s7, v254, 31
	s_cselect_b32 s7, s7, 15
	s_and_b32 s8, s6, s8
	s_cmp_eq_u32 s8, 0
	v_readlane_b32 s8, v254, 33
	s_cselect_b32 s7, s8, s7
	v_readlane_b32 s8, v254, 36
	s_and_b32 s8, s6, s8
	s_cmp_eq_u32 s8, 0
	v_readlane_b32 s8, v254, 35
	s_cselect_b32 s7, s8, s7
	v_readlane_b32 s8, v254, 38
	s_and_b32 s8, s6, s8
	s_cmp_eq_u32 s8, 0
	v_readlane_b32 s8, v254, 37
	s_cselect_b32 s7, s8, s7
	v_readlane_b32 s8, v254, 40
	s_and_b32 s8, s6, s8
	s_cmp_eq_u32 s8, 0
	v_readlane_b32 s8, v254, 39
	s_cselect_b32 s7, s8, s7
	v_readlane_b32 s8, v254, 42
	s_and_b32 s8, s6, s8
	s_cmp_eq_u32 s8, 0
	v_readlane_b32 s8, v254, 41
	s_cselect_b32 s7, s8, s7
	v_readlane_b32 s8, v254, 44
	s_and_b32 s8, s6, s8
	s_cmp_eq_u32 s8, 0
	v_readlane_b32 s8, v254, 43
	s_cselect_b32 s7, s8, s7
	v_readlane_b32 s8, v254, 46
	s_and_b32 s8, s6, s8
	s_cmp_eq_u32 s8, 0
	v_readlane_b32 s8, v254, 45
	s_cselect_b32 s7, s8, s7
	s_bitcmp0_b32 s6, 8
	s_cselect_b32 s6, 8, 15
	s_cmp_eq_u32 s7, 15
	s_cselect_b32 s10, s6, s7
	s_cmp_eq_u32 s10, 15
	s_cbranch_scc1 .LBB0_384
	s_mov_b64 s[8:9], exec
	v_mbcnt_lo_u32_b32 v34, s8, 0
	v_mbcnt_hi_u32_b32 v34, s9, v34
	v_cmp_eq_u32_e32 vcc, 0, v34
	s_and_saveexec_b64 s[6:7], vcc
	s_cbranch_execz .LBB0_383
	s_lshl_b32 s11, s10, 6
	s_add_i32 s11, s11, 64
	s_cmp_lt_u32 s10, 8
	s_cselect_b32 s80, s11, 0
	s_lshl_b64 s[12:13], s[80:81], 2
	v_readlane_b32 s14, v254, 51
	v_readlane_b32 s15, v254, 52
	s_add_u32 s12, s14, s12
	s_addc_u32 s13, s15, s13
	s_bcnt1_i32_b64 s8, s[8:9]
	v_mov_b32_e32 v253, s8
	global_atomic_add v253, v1, v253, s[12:13] sc0
.LBB0_383:
	s_or_b64 exec, exec, s[6:7]
	s_lshl_b32 s6, s10, 16
	v_mov_b32_e32 v95, s6
.LBB0_384:
	s_or_b64 exec, exec, s[4:5]
	v_lshl_add_u64 v[34:35], v[120:121], 1, s[2:3]
	s_waitcnt lgkmcnt(9)
	v_lshlrev_b64 v[46:47], 1, v[114:115]
	v_lshl_add_u64 v[34:35], v[34:35], 0, v[46:47]
	s_mov_b64 s[2:3], 0x3000000
	v_lshl_add_u64 v[36:37], v[34:35], 0, s[2:3]
	v_add_co_u32_e32 v34, vcc, 0x3000000, v34
	v_readlane_b32 s2, v255, 49
	s_nop 0
	v_addc_co_u32_e32 v35, vcc, 0, v35, vcc
	s_waitcnt lgkmcnt(7)
	global_load_dwordx4 v[48:51], v[34:35], off
	global_load_dwordx4 v[42:45], v[36:37], off offset:64
	global_load_dwordx4 v[38:41], v[36:37], off offset:32
	s_nop 0
	global_load_dwordx4 v[34:37], v[36:37], off offset:96
	v_lshl_add_u32 v0, s2, 11, v0
	s_waitcnt lgkmcnt(6)
	v_lshlrev_b64 v[52:53], 11, v[0:1]
	v_readlane_b32 s2, v255, 50
	v_lshl_add_u64 v[52:53], s[56:57], 0, v[52:53]
	s_lshl_b32 s80, s2, 7
	v_lshl_add_u64 v[52:53], v[52:53], 0, s[80:81]
	v_lshl_add_u64 v[46:47], v[52:53], 0, v[46:47]
	s_waitcnt vmcnt(0) lgkmcnt(0)
	s_barrier
	v_min_u32_e32 v253, 0xffff, v253
	v_or_b32_e32 v95, v95, v253
	s_mov_b64 s[2:3], 0
	s_waitcnt vmcnt(3)
	v_mov_b32_e32 v0, v50
	s_nop 1
	v_permlane32_swap_b32_e32 v48, v0
	v_lshlrev_b32_e32 v50, 16, v48
	s_waitcnt lgkmcnt(3)
	v_mov_b32_e32 v54, v51
	v_and_b32_e32 v51, 0xffff0000, v48
	v_mul_f32_e32 v48, 0xbfb8aa3b, v50
	v_exp_f32_e32 v48, v48
	v_permlane32_swap_b32_e32 v49, v54
	v_add_f32_e32 v48, 1.0, v48
	v_rcp_f32_e32 v52, v48
	v_mul_f32_e32 v48, 0xbfb8aa3b, v51
	v_exp_f32_e32 v48, v48
	s_nop 0
	v_add_f32_e32 v48, 1.0, v48
	v_rcp_f32_e32 v53, v48
	v_lshlrev_b32_e32 v48, 16, v49
	v_and_b32_e32 v49, 0xffff0000, v49
	v_mul_f32 v50, v52, v50
	v_mul_f32 v51, v53, v51
	s_nop 0
	v_mul_f32 v18, v18, v50
	v_mul_f32 v19, v19, v51
	s_nop 0
	v_cvt_pk_bf16_f32 v18, v18, v19
	v_mul_f32_e32 v19, 0xbfb8aa3b, v48
	v_exp_f32_e32 v19, v19
	s_nop 0
	v_add_f32_e32 v19, 1.0, v19
	v_rcp_f32_e32 v50, v19
	v_mul_f32_e32 v19, 0xbfb8aa3b, v49
	v_exp_f32_e32 v19, v19
	s_nop 0
	v_add_f32_e32 v19, 1.0, v19
	v_rcp_f32_e32 v51, v19
	s_nop 0
	v_mul_f32 v48, v50, v48
	v_mul_f32 v49, v51, v49
	s_nop 0
	v_mul_f32 v20, v20, v48
	v_mul_f32 v21, v21, v49
	s_nop 0
	v_cvt_pk_bf16_f32 v19, v20, v21
	v_lshlrev_b32_e32 v20, 16, v0
	v_and_b32_e32 v21, 0xffff0000, v0
	v_mul_f32_e32 v0, 0xbfb8aa3b, v20
	v_exp_f32_e32 v0, v0
	s_nop 0
	v_add_f32_e32 v0, 1.0, v0
	v_rcp_f32_e32 v48, v0
	v_mul_f32_e32 v0, 0xbfb8aa3b, v21
	v_exp_f32_e32 v0, v0
	s_nop 0
	v_add_f32_e32 v0, 1.0, v0
	v_rcp_f32_e32 v49, v0
	s_nop 0
	v_mul_f32 v20, v48, v20
	v_mul_f32 v21, v49, v21
	s_nop 0
	v_mul_f32 v20, v22, v20
	v_mul_f32 v21, v23, v21
	v_lshlrev_b32_e32 v22, 16, v54
	v_mul_f32_e32 v0, 0xbfb8aa3b, v22
	v_exp_f32_e32 v0, v0
	v_and_b32_e32 v23, 0xffff0000, v54
	v_cvt_pk_bf16_f32 v20, v20, v21
	s_nop 1
	v_permlane32_swap_b32_e32 v18, v20
	v_add_f32_e32 v0, 1.0, v0
	v_rcp_f32_e32 v48, v0
	v_mul_f32_e32 v0, 0xbfb8aa3b, v23
	v_exp_f32_e32 v0, v0
	s_nop 0
	v_add_f32_e32 v0, 1.0, v0
	v_rcp_f32_e32 v49, v0
	s_waitcnt vmcnt(2)
	v_mov_b32_e32 v0, v44
	s_nop 1
	v_permlane32_swap_b32_e32 v42, v0
	v_mul_f32 v22, v48, v22
	v_mul_f32 v23, v49, v23
	s_nop 0
	v_mul_f32 v22, v24, v22
	v_mul_f32 v23, v25, v23
	s_nop 0
	v_cvt_pk_bf16_f32 v21, v22, v23
	s_nop 1
	v_permlane32_swap_b32_e32 v19, v21
	global_store_dwordx4 v[46:47], v[18:21], off
	v_mov_b32_e32 v22, v45
	s_nop 1
	v_permlane32_swap_b32_e32 v43, v22
	v_lshlrev_b32_e32 v18, 16, v42
	v_and_b32_e32 v19, 0xffff0000, v42
	v_mul_f32_e32 v20, 0xbfb8aa3b, v18
	v_mul_f32_e32 v21, 0xbfb8aa3b, v19
	v_exp_f32_e32 v20, v20
	v_exp_f32_e32 v21, v21
	v_add_f32_e32 v20, 1.0, v20
	v_add_f32_e32 v21, 1.0, v21
	v_rcp_f32_e32 v20, v20
	v_rcp_f32_e32 v21, v21
	s_nop 0
	v_mul_f32 v18, v20, v18
	v_mul_f32 v19, v21, v19
	s_nop 0
	v_mul_f32 v2, v2, v18
	v_mul_f32 v3, v3, v19
	v_lshlrev_b32_e32 v18, 16, v43
	v_cvt_pk_bf16_f32 v2, v2, v3
	v_mul_f32_e32 v3, 0xbfb8aa3b, v18
	v_exp_f32_e32 v3, v3
	v_and_b32_e32 v19, 0xffff0000, v43
	v_add_f32_e32 v3, 1.0, v3
	v_rcp_f32_e32 v20, v3
	v_mul_f32_e32 v3, 0xbfb8aa3b, v19
	v_exp_f32_e32 v3, v3
	s_nop 0
	v_add_f32_e32 v3, 1.0, v3
	v_rcp_f32_e32 v21, v3
	s_nop 0
	v_mul_f32 v18, v20, v18
	v_mul_f32 v19, v21, v19
	s_nop 0
	v_mul_f32 v4, v4, v18
	v_mul_f32 v5, v5, v19
	s_nop 0
	v_cvt_pk_bf16_f32 v3, v4, v5
	v_lshlrev_b32_e32 v4, 16, v0
	v_and_b32_e32 v5, 0xffff0000, v0
	v_mul_f32_e32 v0, 0xbfb8aa3b, v4
	v_exp_f32_e32 v0, v0
	s_nop 0
	v_add_f32_e32 v0, 1.0, v0
	v_rcp_f32_e32 v18, v0
	v_mul_f32_e32 v0, 0xbfb8aa3b, v5
	v_exp_f32_e32 v0, v0
	s_nop 0
	v_add_f32_e32 v0, 1.0, v0
	v_rcp_f32_e32 v19, v0
	s_nop 0
	v_mul_f32 v4, v18, v4
	v_mul_f32 v5, v19, v5
	s_nop 0
	v_mul_f32 v4, v6, v4
	v_mul_f32 v5, v7, v5
	v_lshlrev_b32_e32 v6, 16, v22
	v_mul_f32_e32 v0, 0xbfb8aa3b, v6
	v_exp_f32_e32 v0, v0
	v_and_b32_e32 v7, 0xffff0000, v22
	v_cvt_pk_bf16_f32 v4, v4, v5
	s_nop 1
	v_permlane32_swap_b32_e32 v2, v4
	v_add_f32_e32 v0, 1.0, v0
	v_rcp_f32_e32 v18, v0
	v_mul_f32_e32 v0, 0xbfb8aa3b, v7
	v_exp_f32_e32 v0, v0
	s_nop 0
	v_add_f32_e32 v0, 1.0, v0
	v_rcp_f32_e32 v19, v0
	s_waitcnt vmcnt(2)
	v_mov_b32_e32 v0, v40
	s_nop 1
	v_permlane32_swap_b32_e32 v38, v0
	v_mul_f32 v6, v18, v6
	v_mul_f32 v7, v19, v7
	s_nop 0
	v_mul_f32 v6, v8, v6
	v_mul_f32 v7, v9, v7
	v_mov_b32_e32 v8, v41
	v_cvt_pk_bf16_f32 v5, v6, v7
	s_nop 1
	v_permlane32_swap_b32_e32 v3, v5
	global_store_dwordx4 v[46:47], v[2:5], off offset:64
	v_permlane32_swap_b32_e32 v39, v8
	s_nop 0
	v_lshlrev_b32_e32 v2, 16, v38
	v_and_b32_e32 v3, 0xffff0000, v38
	v_mul_f32_e32 v4, 0xbfb8aa3b, v2
	v_mul_f32_e32 v5, 0xbfb8aa3b, v3
	v_exp_f32_e32 v4, v4
	v_exp_f32_e32 v5, v5
	v_add_f32_e32 v4, 1.0, v4
	v_add_f32_e32 v5, 1.0, v5
	v_rcp_f32_e32 v4, v4
	v_rcp_f32_e32 v5, v5
	s_nop 0
	v_mul_f32 v2, v4, v2
	v_mul_f32 v3, v5, v3
	s_nop 0
	v_mul_f32 v2, v26, v2
	v_mul_f32 v3, v27, v3
	v_lshlrev_b32_e32 v4, 16, v39
	v_cvt_pk_bf16_f32 v2, v2, v3
	v_mul_f32_e32 v3, 0xbfb8aa3b, v4
	v_exp_f32_e32 v3, v3
	v_and_b32_e32 v5, 0xffff0000, v39
	v_add_f32_e32 v3, 1.0, v3
	v_rcp_f32_e32 v6, v3
	v_mul_f32_e32 v3, 0xbfb8aa3b, v5
	v_exp_f32_e32 v3, v3
	s_nop 0
	v_add_f32_e32 v3, 1.0, v3
	v_rcp_f32_e32 v7, v3
	s_nop 0
	v_mul_f32 v4, v6, v4
	v_mul_f32 v5, v7, v5
	s_nop 0
	v_mul_f32 v4, v28, v4
	v_mul_f32 v5, v29, v5
	s_nop 0
	v_cvt_pk_bf16_f32 v3, v4, v5
	v_lshlrev_b32_e32 v4, 16, v0
	v_and_b32_e32 v5, 0xffff0000, v0
	v_mul_f32_e32 v0, 0xbfb8aa3b, v4
	v_exp_f32_e32 v0, v0
	s_nop 0
	v_add_f32_e32 v0, 1.0, v0
	v_rcp_f32_e32 v6, v0
	v_mul_f32_e32 v0, 0xbfb8aa3b, v5
	v_exp_f32_e32 v0, v0
	s_nop 0
	v_add_f32_e32 v0, 1.0, v0
	v_rcp_f32_e32 v7, v0
	s_nop 0
	v_mul_f32 v4, v6, v4
	v_mul_f32 v5, v7, v5
	v_lshlrev_b32_e32 v6, 16, v8
	v_mul_f32_e32 v0, 0xbfb8aa3b, v6
	v_exp_f32_e32 v0, v0
	v_and_b32_e32 v7, 0xffff0000, v8
	v_mul_f32 v4, v30, v4
	v_mul_f32 v5, v31, v5
	v_add_f32_e32 v0, 1.0, v0
	v_rcp_f32_e32 v8, v0
	v_mul_f32_e32 v0, 0xbfb8aa3b, v7
	v_exp_f32_e32 v0, v0
	v_cvt_pk_bf16_f32 v4, v4, v5
	s_nop 1
	v_permlane32_swap_b32_e32 v2, v4
	v_add_f32_e32 v0, 1.0, v0
	v_rcp_f32_e32 v9, v0
	s_waitcnt vmcnt(2)
	v_mov_b32_e32 v0, v36
	s_nop 1
	v_permlane32_swap_b32_e32 v34, v0
	v_mul_f32 v6, v8, v6
	v_mul_f32 v7, v9, v7
	v_mov_b32_e32 v8, v37
	v_mul_f32 v6, v32, v6
	v_mul_f32 v7, v33, v7
	s_nop 0
	v_permlane32_swap_b32_e32 v35, v8
	v_cvt_pk_bf16_f32 v5, v6, v7
	s_nop 1
	v_permlane32_swap_b32_e32 v3, v5
	global_store_dwordx4 v[46:47], v[2:5], off offset:32
	s_nop 1
	v_lshlrev_b32_e32 v2, 16, v34
	v_and_b32_e32 v3, 0xffff0000, v34
	v_mul_f32_e32 v4, 0xbfb8aa3b, v2
	v_mul_f32_e32 v5, 0xbfb8aa3b, v3
	v_exp_f32_e32 v4, v4
	v_exp_f32_e32 v5, v5
	v_add_f32_e32 v4, 1.0, v4
	v_add_f32_e32 v5, 1.0, v5
	v_rcp_f32_e32 v4, v4
	v_rcp_f32_e32 v5, v5
	s_nop 0
	v_mul_f32 v2, v4, v2
	v_mul_f32 v3, v5, v3
	s_nop 0
	v_mul_f32 v2, v10, v2
	v_mul_f32 v3, v11, v3
	v_lshlrev_b32_e32 v4, 16, v35
	v_cvt_pk_bf16_f32 v2, v2, v3
	v_mul_f32_e32 v3, 0xbfb8aa3b, v4
	v_exp_f32_e32 v3, v3
	v_and_b32_e32 v5, 0xffff0000, v35
	v_add_f32_e32 v3, 1.0, v3
	v_rcp_f32_e32 v6, v3
	v_mul_f32_e32 v3, 0xbfb8aa3b, v5
	v_exp_f32_e32 v3, v3
	s_nop 0
	v_add_f32_e32 v3, 1.0, v3
	v_rcp_f32_e32 v7, v3
	s_nop 0
	v_mul_f32 v4, v6, v4
	v_mul_f32 v5, v7, v5
	s_nop 0
	v_mul_f32 v4, v12, v4
	v_mul_f32 v5, v13, v5
	s_nop 0
	v_cvt_pk_bf16_f32 v3, v4, v5
	v_lshlrev_b32_e32 v4, 16, v0
	v_and_b32_e32 v5, 0xffff0000, v0
	v_mul_f32_e32 v0, 0xbfb8aa3b, v4
	v_exp_f32_e32 v0, v0
	s_nop 0
	v_add_f32_e32 v0, 1.0, v0
	v_rcp_f32_e32 v6, v0
	v_mul_f32_e32 v0, 0xbfb8aa3b, v5
	v_exp_f32_e32 v0, v0
	s_nop 0
	v_add_f32_e32 v0, 1.0, v0
	v_rcp_f32_e32 v7, v0
	s_nop 0
	v_mul_f32 v4, v6, v4
	v_mul_f32 v5, v7, v5
	v_lshlrev_b32_e32 v6, 16, v8
	v_mul_f32_e32 v0, 0xbfb8aa3b, v6
	v_exp_f32_e32 v0, v0
	v_and_b32_e32 v7, 0xffff0000, v8
	v_mul_f32 v4, v14, v4
	v_mul_f32 v5, v15, v5
	v_add_f32_e32 v0, 1.0, v0
	v_rcp_f32_e32 v8, v0
	v_mul_f32_e32 v0, 0xbfb8aa3b, v7
	v_exp_f32_e32 v0, v0
	v_cvt_pk_bf16_f32 v4, v4, v5
	s_nop 1
	v_permlane32_swap_b32_e32 v2, v4
	v_add_f32_e32 v0, 1.0, v0
	v_rcp_f32_e32 v9, v0
	s_nop 0
	v_mul_f32 v6, v8, v6
	v_mul_f32 v7, v9, v7
	s_nop 0
	v_mul_f32 v6, v16, v6
	v_mul_f32 v7, v17, v7
	s_nop 0
	v_cvt_pk_bf16_f32 v5, v6, v7
	s_nop 1
	v_permlane32_swap_b32_e32 v3, v5
	global_store_dwordx4 v[46:47], v[2:5], off offset:96

.LBB0_451:
	v_mbcnt_lo_u32_b32 v0, -1, 0
	v_mbcnt_hi_u32_b32 v0, -1, v0
	v_readlane_b32 s2, v254, 2
	v_sub_u32_e32 v0, 0, v0
	v_mov_b32_e32 v95, 0xf0000
	v_cmp_eq_u32_e32 vcc, s2, v0
	s_and_saveexec_b64 s[2:3], vcc
	s_cbranch_execz .LBB0_456
	v_mov_b32_e32 v0, s69
	ds_read_b32 v0, v0
	v_readlane_b32 s5, v254, 32
	v_readlane_b32 s8, v254, 34
	v_mov_b32_e32 v95, 0xf0000
	s_waitcnt lgkmcnt(0)
	v_readfirstlane_b32 s4, v0
	s_and_b32 s5, s4, s5
	s_cmp_eq_u32 s5, 0
	v_readlane_b32 s5, v254, 31
	s_cselect_b32 s5, s5, 15
	s_and_b32 s8, s4, s8
	s_cmp_eq_u32 s8, 0
	v_readlane_b32 s8, v254, 33
	s_cselect_b32 s5, s8, s5
	v_readlane_b32 s8, v254, 36
	s_and_b32 s8, s4, s8
	s_cmp_eq_u32 s8, 0
	v_readlane_b32 s8, v254, 35
	s_cselect_b32 s5, s8, s5
	v_readlane_b32 s8, v254, 38
	s_and_b32 s8, s4, s8
	s_cmp_eq_u32 s8, 0
	v_readlane_b32 s8, v254, 37
	s_cselect_b32 s5, s8, s5
	v_readlane_b32 s8, v254, 40
	s_and_b32 s8, s4, s8
	s_cmp_eq_u32 s8, 0
	v_readlane_b32 s8, v254, 39
	s_cselect_b32 s5, s8, s5
	v_readlane_b32 s8, v254, 42
	s_and_b32 s8, s4, s8
	s_cmp_eq_u32 s8, 0
	v_readlane_b32 s8, v254, 41
	s_cselect_b32 s5, s8, s5
	v_readlane_b32 s8, v254, 44
	s_and_b32 s8, s4, s8
	s_cmp_eq_u32 s8, 0
	v_readlane_b32 s8, v254, 43
	s_cselect_b32 s5, s8, s5
	v_readlane_b32 s8, v254, 46
	s_and_b32 s8, s4, s8
	s_cmp_eq_u32 s8, 0
	v_readlane_b32 s8, v254, 45
	s_cselect_b32 s5, s8, s5
	s_bitcmp0_b32 s4, 8
	s_cselect_b32 s4, 8, 15
	s_cmp_eq_u32 s5, 15
	s_cselect_b32 s10, s4, s5
	s_cmp_eq_u32 s10, 15
	s_cbranch_scc1 .LBB0_456
	s_mov_b64 s[8:9], exec
	v_mbcnt_lo_u32_b32 v0, s8, 0
	v_mbcnt_hi_u32_b32 v0, s9, v0
	v_cmp_eq_u32_e32 vcc, 0, v0
	s_and_saveexec_b64 s[4:5], vcc
	s_cbranch_execz .LBB0_455
	s_lshl_b32 s11, s10, 6
	s_add_i32 s11, s11, 64
	s_cmp_lt_u32 s10, 8
	s_cselect_b32 s80, s11, 0
	s_lshl_b64 s[12:13], s[80:81], 2
	v_readlane_b32 s14, v254, 51
	v_readlane_b32 s15, v254, 52
	s_add_u32 s12, s14, s12
	s_addc_u32 s13, s15, s13
	s_bcnt1_i32_b64 s8, s[8:9]
	v_mov_b32_e32 v253, s8
	global_atomic_add v253, v1, v253, s[12:13] sc0
.LBB0_455:
	s_or_b64 exec, exec, s[4:5]
	s_lshl_b32 s4, s10, 16
	v_mov_b32_e32 v95, s4

.LBB0_458:
	v_readlane_b32 s2, v255, 27
	s_waitcnt vmcnt(0) lgkmcnt(0)
	s_barrier
	v_min_u32_e32 v253, 0xffff, v253
	v_or_b32_e32 v95, v95, v253
	v_readlane_b32 s3, v255, 28
	s_andn2_b64 vcc, exec, s[2:3]
	v_readlane_b32 s2, v255, 25
	s_nop 1
	v_lshl_add_u32 v0, v216, 2, s2
	s_cbranch_vccnz .LBB0_460
	v_readlane_b32 s2, v255, 31
	v_mov_b32_e32 v3, v217
	v_mov_b32_e32 v4, v217
	v_mov_b32_e32 v2, s2
	ds_read_b32 v2, v2
	v_permlane32_swap_b32_e32 v3, v4
	v_add_f32_e32 v3, v3, v4
	s_waitcnt lgkmcnt(0)
	v_div_scale_f32 v4, s[2:3], v3, v3, v2
	v_rcp_f32_e32 v5, v4
	s_nop 0
	v_fma_f32 v6, -v4, v5, 1.0
	v_fmac_f32_e32 v5, v6, v5
	v_div_scale_f32 v6, vcc, v2, v3, v2
	v_mul_f32_e32 v7, v6, v5
	v_fma_f32 v8, -v4, v7, v6
	v_fmac_f32_e32 v7, v8, v5
	v_fma_f32 v4, -v4, v7, v6
	v_div_fmas_f32 v4, v4, v5, v7
	v_div_fixup_f32 v2, v4, v3, v2
	v_mul_f32_e32 v3, v64, v2
	v_mul_f32_e32 v4, v65, v2
	ds_write2st64_b32 v0, v3, v4 offset1:1
	v_mul_f32_e32 v3, v66, v2
	v_mul_f32_e32 v4, v67, v2
	ds_write2st64_b32 v0, v3, v4 offset0:2 offset1:3
	v_mul_f32_e32 v3, v68, v2
	v_mul_f32_e32 v4, v69, v2
	ds_write2st64_b32 v0, v3, v4 offset0:4 offset1:5
	v_mul_f32_e32 v3, v70, v2
	v_mul_f32_e32 v4, v71, v2
	ds_write2st64_b32 v0, v3, v4 offset0:6 offset1:7
	v_mul_f32_e32 v3, v72, v2
	v_mul_f32_e32 v4, v73, v2
	ds_write2st64_b32 v0, v3, v4 offset0:8 offset1:9
	v_mul_f32_e32 v3, v74, v2
	v_mul_f32_e32 v4, v75, v2
	ds_write2st64_b32 v0, v3, v4 offset0:10 offset1:11
	v_mul_f32_e32 v3, v76, v2
	v_mul_f32_e32 v4, v77, v2
	ds_write2st64_b32 v0, v3, v4 offset0:12 offset1:13
	v_mul_f32_e32 v3, v78, v2
	v_mul_f32_e32 v4, v79, v2
	ds_write2st64_b32 v0, v3, v4 offset0:14 offset1:15
	v_mul_f32_e32 v3, v48, v2
	v_mul_f32_e32 v4, v49, v2
	ds_write2st64_b32 v0, v3, v4 offset0:16 offset1:17
	v_mul_f32_e32 v3, v50, v2
	v_mul_f32_e32 v4, v51, v2
	ds_write2st64_b32 v0, v3, v4 offset0:18 offset1:19
	v_mul_f32_e32 v3, v52, v2
	v_mul_f32_e32 v4, v53, v2
	ds_write2st64_b32 v0, v3, v4 offset0:20 offset1:21
	v_mul_f32_e32 v3, v54, v2
	v_mul_f32_e32 v4, v55, v2
	ds_write2st64_b32 v0, v3, v4 offset0:22 offset1:23
	v_mul_f32_e32 v3, v56, v2
	v_mul_f32_e32 v4, v57, v2
	ds_write2st64_b32 v0, v3, v4 offset0:24 offset1:25
	v_mul_f32_e32 v3, v58, v2
	v_mul_f32_e32 v4, v59, v2
	ds_write2st64_b32 v0, v3, v4 offset0:26 offset1:27
	v_mul_f32_e32 v3, v60, v2
	v_mul_f32_e32 v4, v61, v2
	ds_write2st64_b32 v0, v3, v4 offset0:28 offset1:29
	v_mul_f32_e32 v3, v62, v2
	v_mul_f32_e32 v4, v63, v2
	ds_write2st64_b32 v0, v3, v4 offset0:30 offset1:31
	v_mul_f32_e32 v3, v32, v2
	v_mul_f32_e32 v4, v33, v2
	ds_write2st64_b32 v0, v3, v4 offset0:32 offset1:33
	v_mul_f32_e32 v3, v34, v2
	v_mul_f32_e32 v4, v35, v2
	ds_write2st64_b32 v0, v3, v4 offset0:34 offset1:35
	v_mul_f32_e32 v3, v36, v2
	v_mul_f32_e32 v4, v37, v2
	ds_write2st64_b32 v0, v3, v4 offset0:36 offset1:37
	v_mul_f32_e32 v3, v38, v2
	v_mul_f32_e32 v4, v39, v2
	ds_write2st64_b32 v0, v3, v4 offset0:38 offset1:39
	v_mul_f32_e32 v3, v40, v2
	v_mul_f32_e32 v4, v41, v2
	ds_write2st64_b32 v0, v3, v4 offset0:40 offset1:41
	v_mul_f32_e32 v3, v42, v2
	v_mul_f32_e32 v4, v43, v2
	ds_write2st64_b32 v0, v3, v4 offset0:42 offset1:43
	v_mul_f32_e32 v3, v44, v2
	v_mul_f32_e32 v4, v45, v2
	ds_write2st64_b32 v0, v3, v4 offset0:44 offset1:45
	v_mul_f32_e32 v3, v46, v2
	v_mul_f32_e32 v4, v47, v2
	ds_write2st64_b32 v0, v3, v4 offset0:46 offset1:47
	v_mul_f32_e32 v3, v16, v2
	v_mul_f32_e32 v4, v17, v2
	ds_write2st64_b32 v0, v3, v4 offset0:48 offset1:49
	v_mul_f32_e32 v3, v18, v2
	v_mul_f32_e32 v4, v19, v2
	ds_write2st64_b32 v0, v3, v4 offset0:50 offset1:51
	v_mul_f32_e32 v3, v20, v2
	v_mul_f32_e32 v4, v21, v2
	ds_write2st64_b32 v0, v3, v4 offset0:52 offset1:53
	v_mul_f32_e32 v3, v22, v2
	v_mul_f32_e32 v4, v23, v2
	ds_write2st64_b32 v0, v3, v4 offset0:54 offset1:55
	v_mul_f32_e32 v3, v24, v2
	v_mul_f32_e32 v4, v25, v2
	ds_write2st64_b32 v0, v3, v4 offset0:56 offset1:57
	v_mul_f32_e32 v3, v26, v2
	v_mul_f32_e32 v4, v27, v2
	ds_write2st64_b32 v0, v3, v4 offset0:58 offset1:59
	v_mul_f32_e32 v3, v28, v2
	v_mul_f32_e32 v4, v29, v2
	ds_write2st64_b32 v0, v3, v4 offset0:60 offset1:61
	v_mul_f32_e32 v3, v30, v2
	v_mul_f32_e32 v2, v31, v2
	ds_write2st64_b32 v0, v3, v2 offset0:62 offset1:63

.LBB0_475:
	v_mov_b32_e32 v2, 0
	v_mov_b32_e32 v0, 0
	v_mov_b32_e32 v1, 0
	s_waitcnt vmcnt(0)
	v_readlane_b32 s5, v234, 0
	v_readlane_b32 s7, v240, 0
	v_readlane_b32 s4, v233, 0
	v_readlane_b32 s6, v235, 0
	v_mov_b32_e32 v8, s5
	v_mov_b32_e32 v9, s7
	v_fmac_f32_e32 v1, s4, v8
	v_fmac_f32_e32 v0, s6, v9
	v_readlane_b32 s5, v234, 1
	v_readlane_b32 s7, v240, 1
	v_readlane_b32 s4, v233, 1
	v_readlane_b32 s6, v235, 1
	v_mov_b32_e32 v8, s5
	v_mov_b32_e32 v9, s7
	v_fmac_f32_e32 v1, s4, v8
	v_fmac_f32_e32 v0, s6, v9
	v_readlane_b32 s5, v234, 2
	v_readlane_b32 s7, v240, 2
	v_readlane_b32 s4, v233, 2
	v_readlane_b32 s6, v235, 2
	v_mov_b32_e32 v8, s5
	v_mov_b32_e32 v9, s7
	v_fmac_f32_e32 v1, s4, v8
	v_fmac_f32_e32 v0, s6, v9
	v_readlane_b32 s5, v234, 3
	v_readlane_b32 s7, v240, 3
	v_readlane_b32 s4, v233, 3
	v_readlane_b32 s6, v235, 3
	v_mov_b32_e32 v8, s5
	v_mov_b32_e32 v9, s7
	v_fmac_f32_e32 v1, s4, v8
	v_fmac_f32_e32 v0, s6, v9
	v_readlane_b32 s5, v234, 4
	v_readlane_b32 s7, v240, 4
	v_readlane_b32 s4, v233, 4
	v_readlane_b32 s6, v235, 4
	v_mov_b32_e32 v8, s5
	v_mov_b32_e32 v9, s7
	v_fmac_f32_e32 v1, s4, v8
	v_fmac_f32_e32 v0, s6, v9
	v_readlane_b32 s5, v234, 5
	v_readlane_b32 s7, v240, 5
	v_readlane_b32 s4, v233, 5
	v_readlane_b32 s6, v235, 5
	v_mov_b32_e32 v8, s5
	v_mov_b32_e32 v9, s7
	v_fmac_f32_e32 v1, s4, v8
	v_fmac_f32_e32 v0, s6, v9
	v_readlane_b32 s5, v234, 6
	v_readlane_b32 s7, v240, 6
	v_readlane_b32 s4, v233, 6
	v_readlane_b32 s6, v235, 6
	v_mov_b32_e32 v8, s5
	v_mov_b32_e32 v9, s7
	v_fmac_f32_e32 v1, s4, v8
	v_fmac_f32_e32 v0, s6, v9
	v_readlane_b32 s5, v234, 7
	v_readlane_b32 s7, v240, 7
	v_readlane_b32 s4, v233, 7
	v_readlane_b32 s6, v235, 7
	v_mov_b32_e32 v8, s5
	v_mov_b32_e32 v9, s7
	v_fmac_f32_e32 v1, s4, v8
	v_fmac_f32_e32 v0, s6, v9
	v_readlane_b32 s5, v234, 8
	v_readlane_b32 s7, v240, 8
	v_readlane_b32 s4, v233, 8
	v_readlane_b32 s6, v235, 8
	v_mov_b32_e32 v8, s5
	v_mov_b32_e32 v9, s7
	v_fmac_f32_e32 v1, s4, v8
	v_fmac_f32_e32 v0, s6, v9
	v_readlane_b32 s5, v234, 9
	v_readlane_b32 s7, v240, 9
	v_readlane_b32 s4, v233, 9
	v_readlane_b32 s6, v235, 9
	v_mov_b32_e32 v8, s5
	v_mov_b32_e32 v9, s7
	v_fmac_f32_e32 v1, s4, v8
	v_fmac_f32_e32 v0, s6, v9
	v_readlane_b32 s5, v234, 10
	v_readlane_b32 s7, v240, 10
	v_readlane_b32 s4, v233, 10
	v_readlane_b32 s6, v235, 10
	v_mov_b32_e32 v8, s5
	v_mov_b32_e32 v9, s7
	v_fmac_f32_e32 v1, s4, v8
	v_fmac_f32_e32 v0, s6, v9
	v_readlane_b32 s5, v234, 11
	v_readlane_b32 s7, v240, 11
	v_readlane_b32 s4, v233, 11
	v_readlane_b32 s6, v235, 11
	v_mov_b32_e32 v8, s5
	v_mov_b32_e32 v9, s7
	v_fmac_f32_e32 v1, s4, v8
	v_fmac_f32_e32 v0, s6, v9
	v_readlane_b32 s5, v234, 12
	v_readlane_b32 s7, v240, 12
	v_readlane_b32 s4, v233, 12
	v_readlane_b32 s6, v235, 12
	v_mov_b32_e32 v8, s5
	v_mov_b32_e32 v9, s7
	v_fmac_f32_e32 v1, s4, v8
	v_fmac_f32_e32 v0, s6, v9
	v_readlane_b32 s5, v234, 13
	v_readlane_b32 s7, v240, 13
	v_readlane_b32 s4, v233, 13
	v_readlane_b32 s6, v235, 13
	v_mov_b32_e32 v8, s5
	v_mov_b32_e32 v9, s7
	v_fmac_f32_e32 v1, s4, v8
	v_fmac_f32_e32 v0, s6, v9
	v_readlane_b32 s5, v234, 14
	v_readlane_b32 s7, v240, 14
	v_readlane_b32 s4, v233, 14
	v_readlane_b32 s6, v235, 14
	v_mov_b32_e32 v8, s5
	v_mov_b32_e32 v9, s7
	v_fmac_f32_e32 v1, s4, v8
	v_fmac_f32_e32 v0, s6, v9
	v_readlane_b32 s5, v234, 15
	v_readlane_b32 s7, v240, 15
	v_readlane_b32 s4, v233, 15
	v_readlane_b32 s6, v235, 15
	v_mov_b32_e32 v8, s5
	v_mov_b32_e32 v9, s7
	v_fmac_f32_e32 v1, s4, v8
	v_fmac_f32_e32 v0, s6, v9
	v_readlane_b32 s5, v234, 16
	v_readlane_b32 s7, v240, 16
	v_readlane_b32 s4, v233, 16
	v_readlane_b32 s6, v235, 16
	v_mov_b32_e32 v8, s5
	v_mov_b32_e32 v9, s7
	v_fmac_f32_e32 v1, s4, v8
	v_fmac_f32_e32 v0, s6, v9
	v_readlane_b32 s5, v234, 17
	v_readlane_b32 s7, v240, 17
	v_readlane_b32 s4, v233, 17
	v_readlane_b32 s6, v235, 17
	v_mov_b32_e32 v8, s5
	v_mov_b32_e32 v9, s7
	v_fmac_f32_e32 v1, s4, v8
	v_fmac_f32_e32 v0, s6, v9
	v_readlane_b32 s5, v234, 18
	v_readlane_b32 s7, v240, 18
	v_readlane_b32 s4, v233, 18
	v_readlane_b32 s6, v235, 18
	v_mov_b32_e32 v8, s5
	v_mov_b32_e32 v9, s7
	v_fmac_f32_e32 v1, s4, v8
	v_fmac_f32_e32 v0, s6, v9
	v_readlane_b32 s5, v234, 19
	v_readlane_b32 s7, v240, 19
	v_readlane_b32 s4, v233, 19
	v_readlane_b32 s6, v235, 19
	v_mov_b32_e32 v8, s5
	v_mov_b32_e32 v9, s7
	v_fmac_f32_e32 v1, s4, v8
	v_fmac_f32_e32 v0, s6, v9
	v_readlane_b32 s5, v234, 20
	v_readlane_b32 s7, v240, 20
	v_readlane_b32 s4, v233, 20
	v_readlane_b32 s6, v235, 20
	v_mov_b32_e32 v8, s5
	v_mov_b32_e32 v9, s7
	v_fmac_f32_e32 v1, s4, v8
	v_fmac_f32_e32 v0, s6, v9
	v_readlane_b32 s5, v234, 21
	v_readlane_b32 s7, v240, 21
	v_readlane_b32 s4, v233, 21
	v_readlane_b32 s6, v235, 21
	v_mov_b32_e32 v8, s5
	v_mov_b32_e32 v9, s7
	v_fmac_f32_e32 v1, s4, v8
	v_fmac_f32_e32 v0, s6, v9
	v_readlane_b32 s5, v234, 22
	v_readlane_b32 s7, v240, 22
	v_readlane_b32 s4, v233, 22
	v_readlane_b32 s6, v235, 22
	v_mov_b32_e32 v8, s5
	v_mov_b32_e32 v9, s7
	v_fmac_f32_e32 v1, s4, v8
	v_fmac_f32_e32 v0, s6, v9
	v_readlane_b32 s5, v234, 23
	v_readlane_b32 s7, v240, 23
	v_readlane_b32 s4, v233, 23
	v_readlane_b32 s6, v235, 23
	v_mov_b32_e32 v8, s5
	v_mov_b32_e32 v9, s7
	v_fmac_f32_e32 v1, s4, v8
	v_fmac_f32_e32 v0, s6, v9
	v_readlane_b32 s5, v234, 24
	v_readlane_b32 s7, v240, 24
	v_readlane_b32 s4, v233, 24
	v_readlane_b32 s6, v235, 24
	v_mov_b32_e32 v8, s5
	v_mov_b32_e32 v9, s7
	v_fmac_f32_e32 v1, s4, v8
	v_fmac_f32_e32 v0, s6, v9
	v_readlane_b32 s5, v234, 25
	v_readlane_b32 s7, v240, 25
	v_readlane_b32 s4, v233, 25
	v_readlane_b32 s6, v235, 25
	v_mov_b32_e32 v8, s5
	v_mov_b32_e32 v9, s7
	v_fmac_f32_e32 v1, s4, v8
	v_fmac_f32_e32 v0, s6, v9
	v_readlane_b32 s5, v234, 26
	v_readlane_b32 s7, v240, 26
	v_readlane_b32 s4, v233, 26
	v_readlane_b32 s6, v235, 26
	v_mov_b32_e32 v8, s5
	v_mov_b32_e32 v9, s7
	v_fmac_f32_e32 v1, s4, v8
	v_fmac_f32_e32 v0, s6, v9
	v_readlane_b32 s5, v234, 27
	v_readlane_b32 s7, v240, 27
	v_readlane_b32 s4, v233, 27
	v_readlane_b32 s6, v235, 27
	v_mov_b32_e32 v8, s5
	v_mov_b32_e32 v9, s7
	v_fmac_f32_e32 v1, s4, v8
	v_fmac_f32_e32 v0, s6, v9
	v_readlane_b32 s5, v234, 28
	v_readlane_b32 s7, v240, 28
	v_readlane_b32 s4, v233, 28
	v_readlane_b32 s6, v235, 28
	v_mov_b32_e32 v8, s5
	v_mov_b32_e32 v9, s7
	v_fmac_f32_e32 v1, s4, v8
	v_fmac_f32_e32 v0, s6, v9
	v_readlane_b32 s5, v234, 29
	v_readlane_b32 s7, v240, 29
	v_readlane_b32 s4, v233, 29
	v_readlane_b32 s6, v235, 29
	v_mov_b32_e32 v8, s5
	v_mov_b32_e32 v9, s7
	v_fmac_f32_e32 v1, s4, v8
	v_fmac_f32_e32 v0, s6, v9
	v_readlane_b32 s5, v234, 30
	v_readlane_b32 s7, v240, 30
	v_readlane_b32 s4, v233, 30
	v_readlane_b32 s6, v235, 30
	v_mov_b32_e32 v8, s5
	v_mov_b32_e32 v9, s7
	v_fmac_f32_e32 v1, s4, v8
	v_fmac_f32_e32 v0, s6, v9
	v_readlane_b32 s5, v234, 31
	v_readlane_b32 s7, v240, 31
	v_readlane_b32 s4, v233, 31
	v_readlane_b32 s6, v235, 31
	v_mov_b32_e32 v8, s5
	v_mov_b32_e32 v9, s7
	v_fmac_f32_e32 v1, s4, v8
	v_fmac_f32_e32 v0, s6, v9
	v_readlane_b32 s5, v234, 32
	v_readlane_b32 s7, v240, 32
	v_readlane_b32 s4, v233, 32
	v_readlane_b32 s6, v235, 32
	v_mov_b32_e32 v8, s5
	v_mov_b32_e32 v9, s7
	v_fmac_f32_e32 v1, s4, v8
	v_fmac_f32_e32 v0, s6, v9
	v_readlane_b32 s5, v234, 33
	v_readlane_b32 s7, v240, 33
	v_readlane_b32 s4, v233, 33
	v_readlane_b32 s6, v235, 33
	v_mov_b32_e32 v8, s5
	v_mov_b32_e32 v9, s7
	v_fmac_f32_e32 v1, s4, v8
	v_fmac_f32_e32 v0, s6, v9
	v_readlane_b32 s5, v234, 34
	v_readlane_b32 s7, v240, 34
	v_readlane_b32 s4, v233, 34
	v_readlane_b32 s6, v235, 34
	v_mov_b32_e32 v8, s5
	v_mov_b32_e32 v9, s7
	v_fmac_f32_e32 v1, s4, v8
	v_fmac_f32_e32 v0, s6, v9
	v_readlane_b32 s5, v234, 35
	v_readlane_b32 s7, v240, 35
	v_readlane_b32 s4, v233, 35
	v_readlane_b32 s6, v235, 35
	v_mov_b32_e32 v8, s5
	v_mov_b32_e32 v9, s7
	v_fmac_f32_e32 v1, s4, v8
	v_fmac_f32_e32 v0, s6, v9
	v_readlane_b32 s5, v234, 36
	v_readlane_b32 s7, v240, 36
	v_readlane_b32 s4, v233, 36
	v_readlane_b32 s6, v235, 36
	v_mov_b32_e32 v8, s5
	v_mov_b32_e32 v9, s7
	v_fmac_f32_e32 v1, s4, v8
	v_fmac_f32_e32 v0, s6, v9
	v_readlane_b32 s5, v234, 37
	v_readlane_b32 s7, v240, 37
	v_readlane_b32 s4, v233, 37
	v_readlane_b32 s6, v235, 37
	v_mov_b32_e32 v8, s5
	v_mov_b32_e32 v9, s7
	v_fmac_f32_e32 v1, s4, v8
	v_fmac_f32_e32 v0, s6, v9
	v_readlane_b32 s5, v234, 38
	v_readlane_b32 s7, v240, 38
	v_readlane_b32 s4, v233, 38
	v_readlane_b32 s6, v235, 38
	v_mov_b32_e32 v8, s5
	v_mov_b32_e32 v9, s7
	v_fmac_f32_e32 v1, s4, v8
	v_fmac_f32_e32 v0, s6, v9
	v_readlane_b32 s5, v234, 39
	v_readlane_b32 s7, v240, 39
	v_readlane_b32 s4, v233, 39
	v_readlane_b32 s6, v235, 39
	v_mov_b32_e32 v8, s5
	v_mov_b32_e32 v9, s7
	v_fmac_f32_e32 v1, s4, v8
	v_fmac_f32_e32 v0, s6, v9
	v_readlane_b32 s5, v234, 40
	v_readlane_b32 s7, v240, 40
	v_readlane_b32 s4, v233, 40
	v_readlane_b32 s6, v235, 40
	v_mov_b32_e32 v8, s5
	v_mov_b32_e32 v9, s7
	v_fmac_f32_e32 v1, s4, v8
	v_fmac_f32_e32 v0, s6, v9
	v_readlane_b32 s5, v234, 41
	v_readlane_b32 s7, v240, 41
	v_readlane_b32 s4, v233, 41
	v_readlane_b32 s6, v235, 41
	v_mov_b32_e32 v8, s5
	v_mov_b32_e32 v9, s7
	v_fmac_f32_e32 v1, s4, v8
	v_fmac_f32_e32 v0, s6, v9
	v_readlane_b32 s5, v234, 42
	v_readlane_b32 s7, v240, 42
	v_readlane_b32 s4, v233, 42
	v_readlane_b32 s6, v235, 42
	v_mov_b32_e32 v8, s5
	v_mov_b32_e32 v9, s7
	v_fmac_f32_e32 v1, s4, v8
	v_fmac_f32_e32 v0, s6, v9
	v_readlane_b32 s5, v234, 43
	v_readlane_b32 s7, v240, 43
	v_readlane_b32 s4, v233, 43
	v_readlane_b32 s6, v235, 43
	v_mov_b32_e32 v8, s5
	v_mov_b32_e32 v9, s7
	v_fmac_f32_e32 v1, s4, v8
	v_fmac_f32_e32 v0, s6, v9
	v_readlane_b32 s5, v234, 44
	v_readlane_b32 s7, v240, 44
	v_readlane_b32 s4, v233, 44
	v_readlane_b32 s6, v235, 44
	v_mov_b32_e32 v8, s5
	v_mov_b32_e32 v9, s7
	v_fmac_f32_e32 v1, s4, v8
	v_fmac_f32_e32 v0, s6, v9
	v_readlane_b32 s5, v234, 45
	v_readlane_b32 s7, v240, 45
	v_readlane_b32 s4, v233, 45
	v_readlane_b32 s6, v235, 45
	v_mov_b32_e32 v8, s5
	v_mov_b32_e32 v9, s7
	v_fmac_f32_e32 v1, s4, v8
	v_fmac_f32_e32 v0, s6, v9
	v_readlane_b32 s5, v234, 46
	v_readlane_b32 s7, v240, 46
	v_readlane_b32 s4, v233, 46
	v_readlane_b32 s6, v235, 46
	v_mov_b32_e32 v8, s5
	v_mov_b32_e32 v9, s7
	v_fmac_f32_e32 v1, s4, v8
	v_fmac_f32_e32 v0, s6, v9
	v_readlane_b32 s5, v234, 47
	v_readlane_b32 s7, v240, 47
	v_readlane_b32 s4, v233, 47
	v_readlane_b32 s6, v235, 47
	v_mov_b32_e32 v8, s5
	v_mov_b32_e32 v9, s7
	v_fmac_f32_e32 v1, s4, v8
	v_fmac_f32_e32 v0, s6, v9
	v_readlane_b32 s5, v234, 48
	v_readlane_b32 s7, v240, 48
	v_readlane_b32 s4, v233, 48
	v_readlane_b32 s6, v235, 48
	v_mov_b32_e32 v8, s5
	v_mov_b32_e32 v9, s7
	v_fmac_f32_e32 v1, s4, v8
	v_fmac_f32_e32 v0, s6, v9
	v_readlane_b32 s5, v234, 49
	v_readlane_b32 s7, v240, 49
	v_readlane_b32 s4, v233, 49
	v_readlane_b32 s6, v235, 49
	v_mov_b32_e32 v8, s5
	v_mov_b32_e32 v9, s7
	v_fmac_f32_e32 v1, s4, v8
	v_fmac_f32_e32 v0, s6, v9
	v_readlane_b32 s5, v234, 50
	v_readlane_b32 s7, v240, 50
	v_readlane_b32 s4, v233, 50
	v_readlane_b32 s6, v235, 50
	v_mov_b32_e32 v8, s5
	v_mov_b32_e32 v9, s7
	v_fmac_f32_e32 v1, s4, v8
	v_fmac_f32_e32 v0, s6, v9
	v_readlane_b32 s5, v234, 51
	v_readlane_b32 s7, v240, 51
	v_readlane_b32 s4, v233, 51
	v_readlane_b32 s6, v235, 51
	v_mov_b32_e32 v8, s5
	v_mov_b32_e32 v9, s7
	v_fmac_f32_e32 v1, s4, v8
	v_fmac_f32_e32 v0, s6, v9
	v_readlane_b32 s5, v234, 52
	v_readlane_b32 s7, v240, 52
	v_readlane_b32 s4, v233, 52
	v_readlane_b32 s6, v235, 52
	v_mov_b32_e32 v8, s5
	v_mov_b32_e32 v9, s7
	v_fmac_f32_e32 v1, s4, v8
	v_fmac_f32_e32 v0, s6, v9
	v_readlane_b32 s5, v234, 53
	v_readlane_b32 s7, v240, 53
	v_readlane_b32 s4, v233, 53
	v_readlane_b32 s6, v235, 53
	v_mov_b32_e32 v8, s5
	v_mov_b32_e32 v9, s7
	v_fmac_f32_e32 v1, s4, v8
	v_fmac_f32_e32 v0, s6, v9
	v_readlane_b32 s5, v234, 54
	v_readlane_b32 s7, v240, 54
	v_readlane_b32 s4, v233, 54
	v_readlane_b32 s6, v235, 54
	v_mov_b32_e32 v8, s5
	v_mov_b32_e32 v9, s7
	v_fmac_f32_e32 v1, s4, v8
	v_fmac_f32_e32 v0, s6, v9
	v_readlane_b32 s5, v234, 55
	v_readlane_b32 s7, v240, 55
	v_readlane_b32 s4, v233, 55
	v_readlane_b32 s6, v235, 55
	v_mov_b32_e32 v8, s5
	v_mov_b32_e32 v9, s7
	v_fmac_f32_e32 v1, s4, v8
	v_fmac_f32_e32 v0, s6, v9
	v_readlane_b32 s5, v234, 56
	v_readlane_b32 s7, v240, 56
	v_readlane_b32 s4, v233, 56
	v_readlane_b32 s6, v235, 56
	v_mov_b32_e32 v8, s5
	v_mov_b32_e32 v9, s7
	v_fmac_f32_e32 v1, s4, v8
	v_fmac_f32_e32 v0, s6, v9
	v_readlane_b32 s5, v234, 57
	v_readlane_b32 s7, v240, 57
	v_readlane_b32 s4, v233, 57
	v_readlane_b32 s6, v235, 57
	v_mov_b32_e32 v8, s5
	v_mov_b32_e32 v9, s7
	v_fmac_f32_e32 v1, s4, v8
	v_fmac_f32_e32 v0, s6, v9
	v_readlane_b32 s5, v234, 58
	v_readlane_b32 s7, v240, 58
	v_readlane_b32 s4, v233, 58
	v_readlane_b32 s6, v235, 58
	v_mov_b32_e32 v8, s5
	v_mov_b32_e32 v9, s7
	v_fmac_f32_e32 v1, s4, v8
	v_fmac_f32_e32 v0, s6, v9
	v_readlane_b32 s5, v234, 59
	v_readlane_b32 s7, v240, 59
	v_readlane_b32 s4, v233, 59
	v_readlane_b32 s6, v235, 59
	v_mov_b32_e32 v8, s5
	v_mov_b32_e32 v9, s7
	v_fmac_f32_e32 v1, s4, v8
	v_fmac_f32_e32 v0, s6, v9
	v_readlane_b32 s5, v234, 60
	v_readlane_b32 s7, v240, 60
	v_readlane_b32 s4, v233, 60
	v_readlane_b32 s6, v235, 60
	v_mov_b32_e32 v8, s5
	v_mov_b32_e32 v9, s7
	v_fmac_f32_e32 v1, s4, v8
	v_fmac_f32_e32 v0, s6, v9
	v_readlane_b32 s5, v234, 61
	v_readlane_b32 s7, v240, 61
	v_readlane_b32 s4, v233, 61
	v_readlane_b32 s6, v235, 61
	v_mov_b32_e32 v8, s5
	v_mov_b32_e32 v9, s7
	v_fmac_f32_e32 v1, s4, v8
	v_fmac_f32_e32 v0, s6, v9
	v_readlane_b32 s5, v234, 62
	v_readlane_b32 s7, v240, 62
	v_readlane_b32 s4, v233, 62
	v_readlane_b32 s6, v235, 62
	v_mov_b32_e32 v8, s5
	v_mov_b32_e32 v9, s7
	v_fmac_f32_e32 v1, s4, v8
	v_fmac_f32_e32 v0, s6, v9
	v_readlane_b32 s5, v234, 63
	v_readlane_b32 s7, v240, 63
	v_readlane_b32 s4, v233, 63
	v_readlane_b32 s6, v235, 63
	v_mov_b32_e32 v8, s5
	v_mov_b32_e32 v9, s7
	v_fmac_f32_e32 v1, s4, v8
	v_fmac_f32_e32 v0, s6, v9
	v_cmp_eq_u32_e32 vcc, 0, v231
	s_and_saveexec_b64 s[0:1], vcc
	s_cbranch_execz .LBB0_479
	v_mul_f32_e32 v2, 0x3fb8aa3b, v1
	s_mov_b32 s2, 0x3fb8aa3b
	v_rndne_f32_e32 v3, v2
	v_sub_f32_e32 v4, v2, v3
	v_fma_f32 v2, v1, s2, -v2
	v_fmac_f32_e32 v2, 0x32a5705f, v1
	v_add_f32_e32 v2, v4, v2
	v_exp_f32_e32 v2, v2
	v_cvt_i32_f32_e32 v3, v3
	s_mov_b32 s3, 0xc2ce8ed0
	v_cmp_ngt_f32_e32 vcc, s3, v1
	s_mov_b32 s4, 0x42b17218
	v_ldexp_f32 v2, v2, v3
	v_mul_f32_e32 v3, 0x3fb8aa3b, v0
	v_rndne_f32_e32 v4, v3
	v_sub_f32_e32 v5, v3, v4
	v_fma_f32 v3, v0, s2, -v3
	v_fmac_f32_e32 v3, 0x32a5705f, v0
	v_add_f32_e32 v3, v5, v3
	v_exp_f32_e32 v3, v3
	v_cvt_i32_f32_e32 v4, v4
	v_cndmask_b32_e32 v2, 0, v2, vcc
	v_mov_b32_e32 v5, 0x7f800000
	v_cmp_nlt_f32_e32 vcc, s4, v1
	s_add_i32 s2, 0, 0x24190
	s_nop 0
	v_cndmask_b32_e32 v1, v5, v2, vcc
	v_ldexp_f32 v2, v3, v4
	v_cmp_ngt_f32_e32 vcc, s3, v0
	s_nop 1
	v_cndmask_b32_e32 v2, 0, v2, vcc
	v_cmp_nlt_f32_e32 vcc, s4, v0
	s_nop 1
	v_cndmask_b32_e32 v0, v5, v2, vcc
	v_sub_f32_e32 v0, v1, v0
	v_add_f32_e32 v0, 0x3e4ccccd, v0
	v_mov_b32_e32 v1, s2
	ds_write_b32 v1, v0

.LBB0_485:
	v_readlane_b32 s2, v254, 8
	s_lshl_b32 s2, s2, 8
	v_readlane_b32 s4, v254, 3
	v_readlane_b32 s5, v254, 4
	s_add_u32 s2, s4, s2
	s_addc_u32 s3, s5, 0
	v_mov_b32_e32 v1, 0x1000
	v_mov_b32_e32 v3, 1
	global_atomic_add v3, v1, v3, s[2:3] offset:1024 sc0
	buffer_inv sc1
	v_cvt_f32_u32_e32 v1, v2
	v_sub_u32_e32 v4, 0, v2
	v_rcp_iflag_f32_e32 v1, v1
	s_nop 0
	v_mul_f32_e32 v1, 0x4f7ffffe, v1
	v_cvt_u32_f32_e32 v1, v1
	v_mul_lo_u32 v4, v4, v1
	v_mul_hi_u32 v4, v1, v4
	v_add_u32_e32 v1, v1, v4
	s_waitcnt vmcnt(0)
	v_mul_hi_u32 v1, v3, v1
	v_mul_lo_u32 v4, v1, v2
	v_sub_u32_e32 v4, v3, v4
	v_add_u32_e32 v5, 1, v1
	v_cmp_ge_u32_e32 vcc, v4, v2
	v_add_u32_e32 v3, 1, v3
	s_nop 0
	v_cndmask_b32_e32 v1, v1, v5, vcc
	v_sub_u32_e32 v5, v4, v2
	v_cndmask_b32_e32 v4, v4, v5, vcc
	v_add_u32_e32 v5, 1, v1
	v_cmp_ge_u32_e32 vcc, v4, v2
	s_nop 1
	v_cndmask_b32_e32 v1, v1, v5, vcc
	v_mul_lo_u32 v4, v2, v1
	v_add_u32_e32 v2, v4, v2
	v_cmp_ne_u32_e32 vcc, v3, v2
	s_and_saveexec_b64 s[4:5], vcc
	s_xor_b64 s[4:5], exec, s[4:5]
	s_cbranch_execz .LBB0_499
	s_waitcnt lgkmcnt(0)
	v_mov_b32_e32 v0, 0x2000
	global_load_dword v0, v0, s[2:3] offset:1024 sc1
	s_add_u32 s10, s2, 0x2400
	s_addc_u32 s11, s3, 0
	s_waitcnt vmcnt(0)
	v_cmp_eq_u32_e32 vcc, v0, v1
	s_and_saveexec_b64 s[6:7], vcc
	s_cbranch_execz .LBB0_498
	s_add_u32 s8, s66, 0x4200
	s_addc_u32 s9, s67, 0
	s_mov_b32 s22, 1
	s_mov_b64 s[12:13], 0
	v_mov_b32_e32 v0, 0
	s_branch .LBB0_489

.LBB0_597:
	v_add_u32_e32 v0, s33, v246
	v_ashrrev_i32_e32 v1, 31, v0
	v_lshrrev_b32_e32 v1, 22, v1
	v_add_u32_e32 v1, v0, v1
	v_ashrrev_i32_e32 v8, 10, v1
	v_mul_i32_i24_e32 v1, 0x400, v8
	v_sub_u32_e32 v1, v0, v1
	v_lshrrev_b32_e32 v2, 4, v1
	v_bitop3_b32 v1, v2, v1, 32 bitop3:0x6c
	v_ashrrev_i32_e32 v3, 31, v1
	v_lshrrev_b32_e32 v3, 26, v3
	v_add_u32_e32 v3, v1, v3
	v_ashrrev_i32_e32 v9, 6, v3
	v_and_b32_e32 v3, 0xc0, v3
	v_sub_u32_e32 v1, v1, v3
	v_mov_b32_e32 v3, 1
	v_lshlrev_b32_e32 v2, 3, v8
	v_lshlrev_b32_e32 v4, 5, v8
	v_ashrrev_i16_sdwa v1, v3, sext(v1) dst_sel:DWORD dst_unused:UNUSED_PAD src0_sel:DWORD src1_sel:BYTE_0
	v_and_b32_e32 v2, 0x1ffff0, v2
	v_and_b32_e32 v4, 32, v4
	v_bfe_i32 v10, v1, 0, 16
	v_add_u32_e32 v1, v4, v10
	v_add_lshl_u32 v2, v9, v2, 11
	v_add_u32_e32 v0, 0x2000, v0
	v_lshl_add_u32 v128, v1, 1, v2
	v_ashrrev_i32_e32 v1, 31, v0
	v_lshrrev_b32_e32 v1, 22, v1
	s_add_i32 s0, s2, s0
	v_add_u32_e32 v1, v0, v1
	s_ashr_i32 s1, s0, 31
	v_ashrrev_i32_e32 v11, 10, v1
	s_lshr_b32 s1, s1, 27
	v_mul_i32_i24_e32 v1, 0x400, v11
	s_add_i32 s1, s0, s1
	v_sub_u32_e32 v0, v0, v1
	s_ashr_i32 s2, s1, 5
	s_and_b32 s1, s1, 0xffe0
	v_lshrrev_b32_e32 v1, 4, v0
	s_sub_i32 s1, s0, s1
	v_bitop3_b32 v0, v1, v0, 32 bitop3:0x6c
	s_bfe_i32 s0, s1, 0x80000
	v_ashrrev_i32_e32 v2, 31, v0
	s_bfe_u32 s0, s0, 0x3000c
	v_lshrrev_b32_e32 v2, 26, v2
	s_add_i32 s3, s1, s0
	v_add_u32_e32 v2, v0, v2
	s_bfe_i32 s0, s3, 0x80000
	s_and_b32 s3, s3, 0xf8
	v_ashrrev_i32_e32 v12, 6, v2
	v_and_b32_e32 v2, 0xffc0, v2
	s_sub_i32 s1, s1, s3
	v_sub_u32_e32 v0, v0, v2
	s_lshl_b32 s2, s2, 3
	s_sext_i32_i16 s0, s0
	s_sext_i32_i8 s1, s1
	v_lshrrev_b16_e32 v2, 7, v0
	s_lshr_b32 s0, s0, 3
	s_add_i32 s6, s2, s1
	v_and_b32_e32 v2, 1, v2
	s_ashr_i32 s7, s6, 31
	s_bfe_i64 s[4:5], s[0:1], 0x100000
	v_add_u16_e32 v0, v0, v2
	s_ashr_i32 s9, s63, 2
	s_lshl_b64 s[2:3], s[6:7], 19
	s_lshl_b64 s[4:5], s[4:5], 19
	v_lshlrev_b32_e32 v1, 3, v11
	v_lshlrev_b32_e32 v4, 5, v11
	v_ashrrev_i16_sdwa v0, v3, sext(v0) dst_sel:DWORD dst_unused:UNUSED_PAD src0_sel:DWORD src1_sel:BYTE_0
	s_add_u32 s20, s90, s4
	v_and_b32_e32 v1, 0x1ffff0, v1
	v_and_b32_e32 v4, 32, v4
	v_bfe_i32 v13, v0, 0, 16
	s_addc_u32 s21, s91, s5
	s_add_i32 m0, s76, 0x10000
	v_add_u32_e32 v0, v4, v13
	v_add_lshl_u32 v1, v12, v1, 11
	global_load_lds_dwordx4 v128, s[20:21]
	s_add_i32 m0, s76, 0x12000
	v_lshl_add_u32 v130, v0, 1, v1
	s_add_u32 s4, s20, 0x40000
	global_load_lds_dwordx4 v130, s[20:21]
	s_addc_u32 s5, s21, 0
	s_add_i32 m0, s76, 0x14000
	v_mov_b32_e32 v129, 0
	global_load_lds_dwordx4 v128, s[4:5]
	s_add_i32 m0, s76, 0x16000
	s_add_u32 s2, s78, s2
	s_addc_u32 s3, s79, s3
	s_cmp_lg_u32 s63, 0
	s_cbranch_scc1 .Lph_join
	s_mov_b64 exec, 1
	v_readlane_b32 s34, v254, 8
	s_lshl_b32 s36, s6, 8
	s_and_b32 s34, s34, 7
	s_mul_i32 s34, s34, 3
	s_add_u32 s34, s34, 3
	s_lshl_b32 s35, 1, s34
	s_add_u32 s35, s35, 1
	s_add_u32 s36, s36, 0x8040
	v_mov_b32_e32 v14, s36
	v_mov_b32_e32 v15, s35
	global_atomic_add v14, v15, s[66:67]
	s_lshl_b32 s38, s6, 9
	s_sub_u32 s38, s38, 0x4000
	s_add_u32 s38, s38, 0x8040
	s_add_u32 s39, s38, 0x100
	s_cmp_ge_u32 s6, 32
	s_cselect_b32 s38, s38, s36
	s_cselect_b32 s39, s39, s36
	v_mov_b32_e32 v16, s38
	v_mov_b32_e32 v17, s39
	s_mov_b32 s37, 0
